# same as v30 plus a fallback: grids other than 256 workgroups take the original phase-8 epilogue, seam 8 and phase 9
# speedup vs baseline: 1.0013x; 1.0013x over previous
; #define PG8_STAGE(bufoff, gbase, voff) do { _Pragma("unroll") for (int _i = 0; _i < 2; ++_i) \
;         __builtin_amdgcn_global_load_lds((const unsigned*)((const char*)(gbase) + (voff)[_i]), (PG8_LAS unsigned*)(lds + (bufoff) + ldsw + _i * 8192), 16, 0, 0); } while (0)
; #define PG8_WAIT_V(n) asm volatile("s_waitcnt vmcnt(" #n ")" ::: "memory")
; #define PG8_BAR __builtin_amdgcn_s_barrier()
; template <class Epi, class Sched, bool ALIGN_EPI = false, bool SP2 = false>
; __device__ __forceinline__ void gemm_phase(PG8_LAS unsigned char* lds, const Gemm g, const Sched& S, const Epi& E) {
;     ...
;     for (int i = 0; i < 2; ++i) { int R, C; stage_rc(tid * 16 + i * 8192, R, C); const int Rb = Epi::PERM ? ((R & ~31) + perm32(R & 31)) : R;
;         const int Ra = Epi::APERM ? ((R & ~63) | (4 * (R & 15) + ((R >> 4) & 3))) : R;
;         voffA[i] = Epi::I8 ? (unsigned)(Ra * K + 2 * C) : (unsigned)(Ra * K + C) * 2u; voffB[i] = Epi::I8 ? (unsigned)(Rb * K + 2 * C) : (unsigned)(Rb * K + C) * 2u; }
;     const size_t kstep = (size_t)(BK * 2);
;     const size_t hstep = (size_t)HALF * K * (Epi::I8 ? 1 : 2);
;     const size_t tstep = 2 * hstep;
;     const size_t tstepA = g.a_tstep ? g.a_tstep : tstep;
;     const unsigned ldsw = (unsigned)wid * 1024u;
;     const int aoff = lds_byte(wr * 64 + fr, fq * 8), boff = lds_byte(wc * 32 + fr, fq * 8);
;     ...
;     const char* cA = (const char*)g.A + (size_t)cur.pm * tstepA; const char* cB = (const char*)g.Bt + (size_t)cur.pn * tstep;
;     S.a_ready(cur);
;     if constexpr (SP2) {
;         PG8_STAGE(PG8_SB(0, 0), cB, voffB); PG8_STAGE(PG8_SB(0, 1), cB + hstep, voffB); PG8_STAGE(PG8_SA(0, 0), cA, voffA); PG8_STAGE(PG8_SA(0, 1), cA + hstep, voffA);
;         if (wr == 1) PG8_BAR;
;         PG8_WAIT_V(2); PG8_BAR;
;         PG8_STAGE(PG8_SB(1, 0), cB + kstep, voffB); PG8_STAGE(PG8_SA(1, 0), cA + kstep, voffA); PG8_STAGE(PG8_SB(1, 1), cB + hstep + kstep, voffB);
;         PG8_WAIT_V(6); PG8_BAR;
;     } else {
;         PG8_STAGE(PG8_SB(0, 0), cB, voffB); PG8_STAGE(PG8_SA(0, 0), cA, voffA); PG8_STAGE(PG8_SB(0, 1), cB + hstep, voffB); PG8_STAGE(PG8_SA(0, 1), cA + hstep, voffA);
;         if (wr == 1) PG8_BAR;
;         PG8_WAIT_V(4); PG8_BAR;
.LBB0_1444:
	s_load_dwordx2 s[18:19], s[6:7], 0x98
	s_andn2_b64 vcc, exec, s[8:9]
	s_cbranch_vccnz .LBB0_1480
	s_cmpk_lg_i32 s74, 0x100
	s_cbranch_scc1 .Lrm_skip1
	s_and_b32 s100, s10, 7
	s_lshr_b32 s101, s46, 2
	s_andn2_b32 s10, s10, 7
	s_lshl_b32 s101, s101, 1
	s_add_i32 s10, s10, s101
	s_and_b32 s101, s100, 1
	s_add_i32 s10, s10, s101
	s_lshr_b32 s100, s100, 1
	s_and_b32 s46, s46, 3
	s_lshl_b32 s46, s46, 2
	s_add_i32 s46, s46, s100
.Lrm_skip1:
	s_waitcnt lgkmcnt(0)
	s_add_u32 s3, s14, 0x21a00000
	v_lshlrev_b32_e32 v1, 4, v0
	s_addc_u32 s37, s15, 0
	v_and_b32_e32 v2, 32, v0
	v_or_b32_e32 v13, 0x2000, v1
	s_add_u32 s54, s14, 0x17000000
	v_bfe_u32 v12, v0, 2, 4
	v_bitop3_b32 v10, v1, v2, 48 bitop3:0x6c
	v_lshrrev_b32_e32 v1, 7, v13
	s_movk_i32 s5, 0x70
	s_addc_u32 s55, s15, 0
	v_and_or_b32 v1, v1, s5, v12
	s_lshr_b32 s5, s1, 6
	s_ashr_i32 s11, s10, 31
	s_ashr_i32 s47, s46, 31
	s_lshr_b32 s4, s1, 8
	s_lshl_b32 s56, s5, 10
	s_lshl_b64 s[6:7], s[10:11], 20
	s_lshl_b64 s[8:9], s[46:47], 20
	v_and_b32_e32 v11, 64, v0
	v_lshrrev_b32_e32 v3, 3, v0
	s_add_u32 s50, s54, s8
	v_or_b32_e32 v2, v10, v11
	v_and_or_b32 v3, v3, 48, v12
	s_addc_u32 s51, s55, s9
	s_add_i32 s47, s56, 0
	v_lshl_or_b32 v158, v3, 12, v2
	s_add_i32 m0, s47, 0x10000
	v_lshl_or_b32 v160, v1, 12, v2
	global_load_lds_dwordx4 v158, s[50:51]
	s_add_i32 m0, s47, 0x12000
	s_add_u32 s8, s50, 0x80000
	global_load_lds_dwordx4 v160, s[50:51]
	s_addc_u32 s9, s51, 0
	s_add_i32 m0, s47, 0x14000
	v_mov_b32_e32 v159, 0
	global_load_lds_dwordx4 v158, s[8:9]
	s_add_i32 m0, s47, 0x16000
	s_add_u32 s48, s3, s6
	s_addc_u32 s49, s37, s7
	s_add_i32 s57, s47, 0x2000
	global_load_lds_dwordx4 v160, s[8:9]
	s_mov_b32 m0, s47
	s_add_u32 s6, s48, 0x80000
	global_load_lds_dwordx4 v158, s[48:49]
	s_mov_b32 m0, s57
	s_addc_u32 s7, s49, 0
	s_add_i32 s58, s47, 0x4000
	global_load_lds_dwordx4 v160, s[48:49]
	s_mov_b32 m0, s58
	s_add_i32 s59, s47, 0x6000
	global_load_lds_dwordx4 v158, s[6:7]
	s_mov_b32 m0, s59
	v_mov_b32_e32 v161, v159
	global_load_lds_dwordx4 v160, s[6:7]
	s_cmp_eq_u32 s4, 1
	s_mov_b32 s60, 0
	v_lshl_add_u64 v[8:9], s[50:51], 0, v[158:159]
	v_lshl_add_u64 v[6:7], s[50:51], 0, v[160:161]
	v_lshl_add_u64 v[2:3], s[48:49], 0, v[158:159]
	s_cselect_b64 s[20:21], -1, 0
	s_cmp_lg_u32 s4, 1
	v_lshl_add_u64 v[4:5], s[48:49], 0, v[160:161]
	s_cbranch_scc1 .LBB0_1447
	s_barrier

;     __host__ __device__ bool next(int i, Unit& u) const {
;         const long L = (long)i * G + c; if (L >= nwg) return false;
;         int wgid = (int)L; { const int q = nwg / NXCD, r = nwg % NXCD, xcd = wgid % NXCD, off = wgid / NXCD; wgid = (xcd < r ? xcd * (q + 1) : r * (q + 1) + (xcd - r) * q) + off; }
;         const int nig = wgm * nN, gid = wgid / nig, fm = gid * wgm, gsz = (nM - fm) < wgm ? (nM - fm) : wgm;
;         u.pm = fm + ((wgid % nig) % gsz); u.pn = (wgid % nig) / gsz; return true;
;     }
; template <class Epi, class Sched, bool ALIGN_EPI = false, bool SP2 = false>
; __device__ __forceinline__ void gemm_phase(PG8_LAS unsigned char* lds, const Gemm g, const Sched& S, const Epi& E) {
;     ...
;         const bool has_next = S.next(ui + 1, nxt);
;         const char* nA = has_next ? (const char*)g.A + (size_t)nxt.pm * tstepA : cA; const char* nB = has_next ? (const char*)g.Bt + (size_t)nxt.pn * tstep : cB;
.LBB0_1456:
	s_cmpk_lg_i32 s74, 0x100
	s_cbranch_scc1 .Lrm_skip2
	s_and_b32 s100, s40, 7
	s_lshr_b32 s101, s38, 2
	s_andn2_b32 s40, s40, 7
	s_lshl_b32 s101, s101, 1
	s_add_i32 s40, s40, s101
	s_and_b32 s101, s100, 1
	s_add_i32 s40, s40, s101
	s_lshr_b32 s100, s100, 1
	s_and_b32 s38, s38, 3
	s_lshl_b32 s38, s38, 2
	s_add_i32 s38, s38, s100

; __device__ __forceinline__ f32x4 acc_i2f(const f32x4 a) { return __builtin_convertvector(__builtin_bit_cast(i32x4, a), f32x4); }
;     __device__ __forceinline__ void operator()(const f32x4 (&acc)[2][2][4][2], const pg8::Unit& u, int wr, int wc, int fr, int fq) const {
;         const int row0 = u.pm * 256 + wr * 64 + fr, col0 = u.pn * 256 + wc * 32 + 8 * fq;
;         f32x4 bv[2][2], sb[2][2];
; #pragma unroll
;         for (int bj = 0; bj < 2; ++bj) { bv[bj][0] = *(const f32x4*)(bg + col0 + bj * 128); bv[bj][1] = *(const f32x4*)(bg + col0 + bj * 128 + 4);
;             sb[bj][0] = *(const f32x4*)(cmax + col0 + bj * 128) * (1.f / 127.f); sb[bj][1] = *(const f32x4*)(cmax + col0 + bj * 128 + 4) * (1.f / 127.f); }
; #pragma unroll
;         for (int ai = 0; ai < 2; ++ai)
; #pragma unroll
;             for (int mp = 0; mp < 2; ++mp) {
;                 u32x4 hr[2][2], pr[2][2]; float q1v[2];
; #pragma unroll
;                 for (int mm = 0; mm < 2; ++mm) { const int row = row0 + ai * 128 + (2 * mp + mm) * 16; q1v[mm] = rss1[row];
; #pragma unroll
;                     for (int bj = 0; bj < 2; ++bj) { const size_t off = (size_t)row * DM + col0 + bj * 128; hr[mm][bj] = *(const u32x4*)(HB + off); pr[mm][bj] = *(const u32x4*)(PP + off); } }
; #pragma unroll
;                 for (int mm = 0; mm < 2; ++mm) { const int m = 2 * mp + mm, row = row0 + ai * 128 + m * 16; f32x4 ssv = {0.f, 0.f, 0.f, 0.f}; const float sa = (QCLIP / 127.f) * sqrtf(q1v[mm] * (1.f / DM) + EPS);
; #pragma unroll
;                     for (int bj = 0; bj < 2; ++bj) { const size_t off = (size_t)row * DM + col0 + bj * 128;
;                         f32x4 p0, p1, x0, x1; unpack8v(pr[mm][bj], p0, p1); unpack8v(hr[mm][bj], x0, x1);
;                         const f32x4 g0 = acc_i2f(acc[ai][bj][m][0]) * (sb[bj][0] * sa) + bv[bj][0], g1 = acc_i2f(acc[ai][bj][m][1]) * (sb[bj][1] * sa) + bv[bj][1];
;                         const f32x4 h0 = x0 + p0 * sigm4(g0), h1 = x1 + p1 * sigm4(g1);
;                         *(f32x4*)(H + off) = h0; *(f32x4*)(H + off + 4) = h1;
;                         ssv = ssv + h0 * h0; ssv = ssv + h1 * h1; }
;                     float ss = (ssv[0] + ssv[1]) + (ssv[2] + ssv[3]);
;                     ss += __shfl_xor(ss, 16); ss += __shfl_xor(ss, 32);
;                     if (fq == 0) unsafeAtomicAdd(rss3 + row, ss); }
.LBB0_1460:
	s_cmpk_lg_i32 s74, 0x100
	s_cbranch_scc1 .Lp8_orig_epi
	s_mov_b32 s98, s10
	s_mov_b32 s99, s46
	v_lshlrev_b32_e32 v54, 2, v1
	v_lshlrev_b32_e32 v55, 2, v199
	v_lshlrev_b32_e32 v56, 13, v1
	v_lshlrev_b32_e32 v57, 14, v1
	v_lshl_add_u32 v56, v199, 1, v56
	v_lshl_add_u32 v57, v199, 2, v57
	v_xor_b32_e32 v58, 16, v203
	v_xor_b32_e32 v59, 32, v203
	v_lshlrev_b32_e32 v58, 2, v58
	v_lshlrev_b32_e32 v59, 2, v59
	s_lshl_b32 s48, s99, 10
	s_add_u32 s50, s14, s48
	s_addc_u32 s51, s15, 0
	s_add_u32 s52, s18, s48
	s_addc_u32 s53, s19, 0
	s_lshl_b32 s49, s98, 10
	s_add_u32 s68, s28, s49
	s_addc_u32 s69, s29, 0
	s_add_u32 s70, s26, s49
	s_addc_u32 s71, s27, 0
	s_lshl_b32 s72, s98, 21
	s_lshl_b32 s73, s99, 9
	s_add_u32 s72, s72, s73
	s_add_u32 s86, s22, s72
	s_addc_u32 s87, s23, 0
	s_add_u32 s88, s24, s72
	s_addc_u32 s89, s25, 0
	s_lshl_b32 s72, s98, 22
	s_add_u32 s72, s72, s48
	s_add_u32 s84, s12, s72
	s_addc_u32 s85, s13, 0
	global_load_dwordx4 v[222:225], v55, s[50:51]
	global_load_dwordx4 v[226:229], v55, s[50:51] offset:16
	global_load_dwordx4 v[230:233], v55, s[50:51] offset:512
	global_load_dwordx4 v[234:237], v55, s[50:51] offset:528
	global_load_dwordx4 v[206:209], v55, s[52:53]
	global_load_dwordx4 v[210:213], v55, s[52:53] offset:16
	global_load_dwordx4 v[214:217], v55, s[52:53] offset:512
	global_load_dwordx4 v[218:221], v55, s[52:53] offset:528
	global_load_dword v66, v54, s[68:69]
	global_load_dwordx4 v[238:241], v56, s[86:87]
	global_load_dwordx4 v[242:245], v56, s[86:87] offset:256
	global_load_dwordx4 v[246:249], v56, s[88:89]
	global_load_dwordx4 v[250:253], v56, s[88:89] offset:256
	s_add_u32 s86, s86, 0x20000
	s_addc_u32 s87, s87, 0
	s_add_u32 s88, s88, 0x20000
	s_addc_u32 s89, s89, 0
	global_load_dword v67, v54, s[68:69] offset:64
	global_load_dwordx4 v[170:173], v56, s[86:87]
	global_load_dwordx4 v[174:177], v56, s[86:87] offset:256
	global_load_dwordx4 v[178:181], v56, s[88:89]
	global_load_dwordx4 v[182:185], v56, s[88:89] offset:256
	s_add_u32 s86, s86, 0x20000
	s_addc_u32 s87, s87, 0
	s_add_u32 s88, s88, 0x20000
	s_addc_u32 s89, s89, 0
	s_waitcnt vmcnt(5)
	v_pk_mul_f32 v[222:223], v[222:223], s[36:37] op_sel_hi:[1,0]
	v_pk_mul_f32 v[224:225], v[224:225], s[36:37] op_sel_hi:[1,0]
	v_pk_mul_f32 v[226:227], v[226:227], s[36:37] op_sel_hi:[1,0]
	v_pk_mul_f32 v[228:229], v[228:229], s[36:37] op_sel_hi:[1,0]
	v_pk_mul_f32 v[230:231], v[230:231], s[36:37] op_sel_hi:[1,0]
	v_pk_mul_f32 v[232:233], v[232:233], s[36:37] op_sel_hi:[1,0]
	v_pk_mul_f32 v[234:235], v[234:235], s[36:37] op_sel_hi:[1,0]
	v_pk_mul_f32 v[236:237], v[236:237], s[36:37] op_sel_hi:[1,0]
	v_fmamk_f32 v186, v66, 0x39800000, v204
	v_mul_f32_e32 v187, 0x4f800000, v186
	v_cmp_gt_f32_e32 vcc, s67, v186
	s_nop 1
	v_cndmask_b32_e32 v186, v186, v187, vcc
	v_sqrt_f32_e32 v190, v186
	s_nop 0
	v_add_u32_e32 v191, -1, v190
	v_add_u32_e32 v192, 1, v190
	v_fma_f32 v193, -v191, v190, v186
	v_fma_f32 v187, -v192, v190, v186
	v_cmp_ge_f32_e64 s[10:11], 0, v193
	s_nop 1
	v_cndmask_b32_e64 v190, v190, v191, s[10:11]
	v_cmp_lt_f32_e64 s[10:11], 0, v187
	s_nop 1
	v_cndmask_b32_e64 v190, v190, v192, s[10:11]
	v_mul_f32_e32 v191, 0x37800000, v190
	v_cndmask_b32_e32 v190, v190, v191, vcc
	v_cmp_class_f32_e32 vcc, v186, v205
	s_nop 1
	v_cndmask_b32_e32 v186, v190, v186, vcc
	v_mul_f32_e32 v188, 0x3d112245, v186
	v_cvt_f32_i32_e32 v50, v50
	v_cvt_f32_i32_e32 v51, v51
	v_cvt_f32_i32_e32 v52, v52
	v_cvt_f32_i32_e32 v53, v53
	v_pk_mul_f32 v[142:143], v[222:223], v[188:189] op_sel_hi:[1,0]
	v_pk_mul_f32 v[144:145], v[224:225], v[188:189] op_sel_hi:[1,0]
	v_pk_fma_f32 v[154:155], v[142:143], v[50:51], v[206:207]
	v_pk_fma_f32 v[156:157], v[144:145], v[52:53], v[208:209]
	v_mul_f32_e32 v154, 0xbfb8aa3b, v154
	v_mul_f32_e32 v155, 0xbfb8aa3b, v155
	v_mul_f32_e32 v156, 0xbfb8aa3b, v156
	v_mul_f32_e32 v157, 0xbfb8aa3b, v157
	v_exp_f32_e32 v154, v154
	v_exp_f32_e32 v155, v155
	v_exp_f32_e32 v156, v156
	v_exp_f32_e32 v157, v157
	v_lshlrev_b32_e32 v146, 16, v238
	v_and_b32_e32 v147, 0xffff0000, v238
	v_lshlrev_b32_e32 v148, 16, v239
	v_and_b32_e32 v149, 0xffff0000, v239
	v_add_f32_e32 v154, 1.0, v154
	v_add_f32_e32 v155, 1.0, v155
	v_add_f32_e32 v156, 1.0, v156
	v_add_f32_e32 v157, 1.0, v157
	v_rcp_f32_e32 v154, v154
	v_rcp_f32_e32 v155, v155
	v_rcp_f32_e32 v156, v156
	v_rcp_f32_e32 v157, v157
	v_lshlrev_b32_e32 v150, 16, v246
	v_and_b32_e32 v151, 0xffff0000, v246
	v_lshlrev_b32_e32 v152, 16, v247
	v_and_b32_e32 v153, 0xffff0000, v247
	v_pk_fma_f32 v[50:51], v[154:155], v[150:151], v[146:147]
	v_pk_fma_f32 v[52:53], v[156:157], v[152:153], v[148:149]
	v_pk_mul_f32 v[194:195], v[50:51], v[50:51]
	v_pk_mul_f32 v[196:197], v[52:53], v[52:53]
	v_cvt_f32_i32_e32 v138, v138
	v_cvt_f32_i32_e32 v139, v139
	v_cvt_f32_i32_e32 v140, v140
	v_cvt_f32_i32_e32 v141, v141
	v_pk_mul_f32 v[142:143], v[226:227], v[188:189] op_sel_hi:[1,0]
	v_pk_mul_f32 v[144:145], v[228:229], v[188:189] op_sel_hi:[1,0]
	v_pk_fma_f32 v[154:155], v[142:143], v[138:139], v[210:211]
	v_pk_fma_f32 v[156:157], v[144:145], v[140:141], v[212:213]
	v_mul_f32_e32 v154, 0xbfb8aa3b, v154
	v_mul_f32_e32 v155, 0xbfb8aa3b, v155
	v_mul_f32_e32 v156, 0xbfb8aa3b, v156
	v_mul_f32_e32 v157, 0xbfb8aa3b, v157
	v_exp_f32_e32 v154, v154
	v_exp_f32_e32 v155, v155
	v_exp_f32_e32 v156, v156
	v_exp_f32_e32 v157, v157
	v_lshlrev_b32_e32 v146, 16, v240
	v_and_b32_e32 v147, 0xffff0000, v240
	v_lshlrev_b32_e32 v148, 16, v241
	v_and_b32_e32 v149, 0xffff0000, v241
	v_add_f32_e32 v154, 1.0, v154
	v_add_f32_e32 v155, 1.0, v155
	v_add_f32_e32 v156, 1.0, v156
	v_add_f32_e32 v157, 1.0, v157
	v_rcp_f32_e32 v154, v154
	v_rcp_f32_e32 v155, v155
	v_rcp_f32_e32 v156, v156
; __device__ __forceinline__ f32x4 acc_i2f(const f32x4 a) { return __builtin_convertvector(__builtin_bit_cast(i32x4, a), f32x4); }
;     __device__ __forceinline__ void operator()(const f32x4 (&acc)[2][2][4][2], const pg8::Unit& u, int wr, int wc, int fr, int fq) const {
;     ...
;                 for (int mm = 0; mm < 2; ++mm) { const int m = 2 * mp + mm, row = row0 + ai * 128 + m * 16; f32x4 ssv = {0.f, 0.f, 0.f, 0.f}; const float sa = (QCLIP / 127.f) * sqrtf(q1v[mm] * (1.f / DM) + EPS);
; #pragma unroll
;                     for (int bj = 0; bj < 2; ++bj) { const size_t off = (size_t)row * DM + col0 + bj * 128;
;                         f32x4 p0, p1, x0, x1; unpack8v(pr[mm][bj], p0, p1); unpack8v(hr[mm][bj], x0, x1);
;                         const f32x4 g0 = acc_i2f(acc[ai][bj][m][0]) * (sb[bj][0] * sa) + bv[bj][0], g1 = acc_i2f(acc[ai][bj][m][1]) * (sb[bj][1] * sa) + bv[bj][1];
;                         const f32x4 h0 = x0 + p0 * sigm4(g0), h1 = x1 + p1 * sigm4(g1);
;                         *(f32x4*)(H + off) = h0; *(f32x4*)(H + off + 4) = h1;
;                         ssv = ssv + h0 * h0; ssv = ssv + h1 * h1; }
;                     float ss = (ssv[0] + ssv[1]) + (ssv[2] + ssv[3]);
;                     ss += __shfl_xor(ss, 16); ss += __shfl_xor(ss, 32);
;                     if (fq == 0) unsafeAtomicAdd(rss3 + row, ss); }
	v_rcp_f32_e32 v157, v157
	v_lshlrev_b32_e32 v150, 16, v248
	v_and_b32_e32 v151, 0xffff0000, v248
	v_lshlrev_b32_e32 v152, 16, v249
	v_and_b32_e32 v153, 0xffff0000, v249
	v_pk_fma_f32 v[138:139], v[154:155], v[150:151], v[146:147]
	v_pk_fma_f32 v[140:141], v[156:157], v[152:153], v[148:149]
	v_pk_fma_f32 v[194:195], v[138:139], v[138:139], v[194:195]
	v_pk_fma_f32 v[196:197], v[140:141], v[140:141], v[196:197]
	v_cvt_f32_i32_e32 v134, v134
	v_cvt_f32_i32_e32 v135, v135
	v_cvt_f32_i32_e32 v136, v136
	v_cvt_f32_i32_e32 v137, v137
	v_pk_mul_f32 v[142:143], v[230:231], v[188:189] op_sel_hi:[1,0]
	v_pk_mul_f32 v[144:145], v[232:233], v[188:189] op_sel_hi:[1,0]
	v_pk_fma_f32 v[154:155], v[142:143], v[134:135], v[214:215]
	v_pk_fma_f32 v[156:157], v[144:145], v[136:137], v[216:217]
	v_mul_f32_e32 v154, 0xbfb8aa3b, v154
	v_mul_f32_e32 v155, 0xbfb8aa3b, v155
	v_mul_f32_e32 v156, 0xbfb8aa3b, v156
	v_mul_f32_e32 v157, 0xbfb8aa3b, v157
	v_exp_f32_e32 v154, v154
	v_exp_f32_e32 v155, v155
	v_exp_f32_e32 v156, v156
	v_exp_f32_e32 v157, v157
	v_lshlrev_b32_e32 v146, 16, v242
	v_and_b32_e32 v147, 0xffff0000, v242
	v_lshlrev_b32_e32 v148, 16, v243
	v_and_b32_e32 v149, 0xffff0000, v243
	v_add_f32_e32 v154, 1.0, v154
	v_add_f32_e32 v155, 1.0, v155
	v_add_f32_e32 v156, 1.0, v156
	v_add_f32_e32 v157, 1.0, v157
	v_rcp_f32_e32 v154, v154
	v_rcp_f32_e32 v155, v155
	v_rcp_f32_e32 v156, v156
	v_rcp_f32_e32 v157, v157
	v_lshlrev_b32_e32 v150, 16, v250
	v_and_b32_e32 v151, 0xffff0000, v250
	v_lshlrev_b32_e32 v152, 16, v251
	v_and_b32_e32 v153, 0xffff0000, v251
	v_pk_fma_f32 v[134:135], v[154:155], v[150:151], v[146:147]
	v_pk_fma_f32 v[136:137], v[156:157], v[152:153], v[148:149]
	v_pk_fma_f32 v[194:195], v[134:135], v[134:135], v[194:195]
	v_pk_fma_f32 v[196:197], v[136:137], v[136:137], v[196:197]
	v_cvt_f32_i32_e32 v130, v130
	v_cvt_f32_i32_e32 v131, v131
	v_cvt_f32_i32_e32 v132, v132
	v_cvt_f32_i32_e32 v133, v133
	v_pk_mul_f32 v[142:143], v[234:235], v[188:189] op_sel_hi:[1,0]
	v_pk_mul_f32 v[144:145], v[236:237], v[188:189] op_sel_hi:[1,0]
	v_pk_fma_f32 v[154:155], v[142:143], v[130:131], v[218:219]
	v_pk_fma_f32 v[156:157], v[144:145], v[132:133], v[220:221]
	v_mul_f32_e32 v154, 0xbfb8aa3b, v154
	v_mul_f32_e32 v155, 0xbfb8aa3b, v155
	v_mul_f32_e32 v156, 0xbfb8aa3b, v156
	v_mul_f32_e32 v157, 0xbfb8aa3b, v157
	v_exp_f32_e32 v154, v154
	v_exp_f32_e32 v155, v155
	v_exp_f32_e32 v156, v156
	v_exp_f32_e32 v157, v157
	v_lshlrev_b32_e32 v146, 16, v244
	v_and_b32_e32 v147, 0xffff0000, v244
	v_lshlrev_b32_e32 v148, 16, v245
	v_and_b32_e32 v149, 0xffff0000, v245
	v_add_f32_e32 v154, 1.0, v154
	v_add_f32_e32 v155, 1.0, v155
	v_add_f32_e32 v156, 1.0, v156
	v_add_f32_e32 v157, 1.0, v157
	v_rcp_f32_e32 v154, v154
	v_rcp_f32_e32 v155, v155
	v_rcp_f32_e32 v156, v156
	v_rcp_f32_e32 v157, v157
	v_lshlrev_b32_e32 v150, 16, v252
	v_and_b32_e32 v151, 0xffff0000, v252
	v_lshlrev_b32_e32 v152, 16, v253
	v_and_b32_e32 v153, 0xffff0000, v253
	v_pk_fma_f32 v[130:131], v[154:155], v[150:151], v[146:147]
	v_pk_fma_f32 v[132:133], v[156:157], v[152:153], v[148:149]
	v_pk_fma_f32 v[194:195], v[130:131], v[130:131], v[194:195]
	v_pk_fma_f32 v[196:197], v[132:133], v[132:133], v[196:197]
	v_add_f32_e32 v194, v194, v195
	v_add_f32_e32 v196, v196, v197
	v_add_f32_e32 v194, v194, v196
	ds_bpermute_b32 v195, v58, v194
	s_waitcnt lgkmcnt(0)
	v_add_f32_e32 v194, v194, v195
	ds_bpermute_b32 v195, v59, v194
	s_waitcnt lgkmcnt(0)
	v_add_f32_e32 v194, v194, v195
	s_and_saveexec_b64 s[32:33], s[6:7]
	global_atomic_add_f32 v54, v194, s[70:71]
	s_or_b64 exec, exec, s[32:33]
	global_load_dword v66, v54, s[68:69] offset:128
	global_load_dwordx4 v[238:241], v56, s[86:87]
	global_load_dwordx4 v[242:245], v56, s[86:87] offset:256
	global_load_dwordx4 v[246:249], v56, s[88:89]
	global_load_dwordx4 v[250:253], v56, s[88:89] offset:256
	s_add_u32 s86, s86, 0x20000
	s_addc_u32 s87, s87, 0
	s_add_u32 s88, s88, 0x20000
	s_addc_u32 s89, s89, 0
	s_waitcnt vmcnt(6)
	v_fmamk_f32 v186, v67, 0x39800000, v204
	v_mul_f32_e32 v187, 0x4f800000, v186
	v_cmp_gt_f32_e32 vcc, s67, v186
	s_nop 1
	v_cndmask_b32_e32 v186, v186, v187, vcc
	v_sqrt_f32_e32 v190, v186
	s_nop 0
	v_add_u32_e32 v191, -1, v190
	v_add_u32_e32 v192, 1, v190
	v_fma_f32 v193, -v191, v190, v186
	v_fma_f32 v187, -v192, v190, v186
	v_cmp_ge_f32_e64 s[10:11], 0, v193
	s_nop 1
	v_cndmask_b32_e64 v190, v190, v191, s[10:11]
	v_cmp_lt_f32_e64 s[10:11], 0, v187
	s_nop 1
	v_cndmask_b32_e64 v190, v190, v192, s[10:11]
	v_mul_f32_e32 v191, 0x37800000, v190
	v_cndmask_b32_e32 v190, v190, v191, vcc
	v_cmp_class_f32_e32 vcc, v186, v205
	s_nop 1
	v_cndmask_b32_e32 v186, v190, v186, vcc
	v_mul_f32_e32 v188, 0x3d112245, v186
	v_cvt_f32_i32_e32 v126, v126
	v_cvt_f32_i32_e32 v127, v127
	v_cvt_f32_i32_e32 v128, v128
	v_cvt_f32_i32_e32 v129, v129
	v_pk_mul_f32 v[142:143], v[222:223], v[188:189] op_sel_hi:[1,0]
	v_pk_mul_f32 v[144:145], v[224:225], v[188:189] op_sel_hi:[1,0]
	v_pk_fma_f32 v[154:155], v[142:143], v[126:127], v[206:207]
	v_pk_fma_f32 v[156:157], v[144:145], v[128:129], v[208:209]
	v_mul_f32_e32 v154, 0xbfb8aa3b, v154
	v_mul_f32_e32 v155, 0xbfb8aa3b, v155
	v_mul_f32_e32 v156, 0xbfb8aa3b, v156
	v_mul_f32_e32 v157, 0xbfb8aa3b, v157
	v_exp_f32_e32 v154, v154
	v_exp_f32_e32 v155, v155
	v_exp_f32_e32 v156, v156
	v_exp_f32_e32 v157, v157
	v_lshlrev_b32_e32 v146, 16, v170
	v_and_b32_e32 v147, 0xffff0000, v170
	v_lshlrev_b32_e32 v148, 16, v171
	v_and_b32_e32 v149, 0xffff0000, v171
	v_add_f32_e32 v154, 1.0, v154
	v_add_f32_e32 v155, 1.0, v155
	v_add_f32_e32 v156, 1.0, v156
	v_add_f32_e32 v157, 1.0, v157
	v_rcp_f32_e32 v154, v154
	v_rcp_f32_e32 v155, v155
	v_rcp_f32_e32 v156, v156
; __device__ __forceinline__ f32x4 acc_i2f(const f32x4 a) { return __builtin_convertvector(__builtin_bit_cast(i32x4, a), f32x4); }
;     __device__ __forceinline__ void operator()(const f32x4 (&acc)[2][2][4][2], const pg8::Unit& u, int wr, int wc, int fr, int fq) const {
;     ...
;                 for (int mm = 0; mm < 2; ++mm) { const int m = 2 * mp + mm, row = row0 + ai * 128 + m * 16; f32x4 ssv = {0.f, 0.f, 0.f, 0.f}; const float sa = (QCLIP / 127.f) * sqrtf(q1v[mm] * (1.f / DM) + EPS);
; #pragma unroll
;                     for (int bj = 0; bj < 2; ++bj) { const size_t off = (size_t)row * DM + col0 + bj * 128;
;                         f32x4 p0, p1, x0, x1; unpack8v(pr[mm][bj], p0, p1); unpack8v(hr[mm][bj], x0, x1);
;                         const f32x4 g0 = acc_i2f(acc[ai][bj][m][0]) * (sb[bj][0] * sa) + bv[bj][0], g1 = acc_i2f(acc[ai][bj][m][1]) * (sb[bj][1] * sa) + bv[bj][1];
;                         const f32x4 h0 = x0 + p0 * sigm4(g0), h1 = x1 + p1 * sigm4(g1);
;                         *(f32x4*)(H + off) = h0; *(f32x4*)(H + off + 4) = h1;
;                         ssv = ssv + h0 * h0; ssv = ssv + h1 * h1; }
;                     float ss = (ssv[0] + ssv[1]) + (ssv[2] + ssv[3]);
;                     ss += __shfl_xor(ss, 16); ss += __shfl_xor(ss, 32);
;                     if (fq == 0) unsafeAtomicAdd(rss3 + row, ss); }
	v_rcp_f32_e32 v157, v157
	v_lshlrev_b32_e32 v150, 16, v178
	v_and_b32_e32 v151, 0xffff0000, v178
	v_lshlrev_b32_e32 v152, 16, v179
	v_and_b32_e32 v153, 0xffff0000, v179
	v_pk_fma_f32 v[126:127], v[154:155], v[150:151], v[146:147]
	v_pk_fma_f32 v[128:129], v[156:157], v[152:153], v[148:149]
	v_pk_mul_f32 v[194:195], v[126:127], v[126:127]
	v_pk_mul_f32 v[196:197], v[128:129], v[128:129]
	v_cvt_f32_i32_e32 v122, v122
	v_cvt_f32_i32_e32 v123, v123
	v_cvt_f32_i32_e32 v124, v124
	v_cvt_f32_i32_e32 v125, v125
	v_pk_mul_f32 v[142:143], v[226:227], v[188:189] op_sel_hi:[1,0]
	v_pk_mul_f32 v[144:145], v[228:229], v[188:189] op_sel_hi:[1,0]
	v_pk_fma_f32 v[154:155], v[142:143], v[122:123], v[210:211]
	v_pk_fma_f32 v[156:157], v[144:145], v[124:125], v[212:213]
	v_mul_f32_e32 v154, 0xbfb8aa3b, v154
	v_mul_f32_e32 v155, 0xbfb8aa3b, v155
	v_mul_f32_e32 v156, 0xbfb8aa3b, v156
	v_mul_f32_e32 v157, 0xbfb8aa3b, v157
	v_exp_f32_e32 v154, v154
	v_exp_f32_e32 v155, v155
	v_exp_f32_e32 v156, v156
	v_exp_f32_e32 v157, v157
	v_lshlrev_b32_e32 v146, 16, v172
	v_and_b32_e32 v147, 0xffff0000, v172
	v_lshlrev_b32_e32 v148, 16, v173
	v_and_b32_e32 v149, 0xffff0000, v173
	v_add_f32_e32 v154, 1.0, v154
	v_add_f32_e32 v155, 1.0, v155
	v_add_f32_e32 v156, 1.0, v156
	v_add_f32_e32 v157, 1.0, v157
	v_rcp_f32_e32 v154, v154
	v_rcp_f32_e32 v155, v155
	v_rcp_f32_e32 v156, v156
	v_rcp_f32_e32 v157, v157
	v_lshlrev_b32_e32 v150, 16, v180
	v_and_b32_e32 v151, 0xffff0000, v180
	v_lshlrev_b32_e32 v152, 16, v181
	v_and_b32_e32 v153, 0xffff0000, v181
	v_pk_fma_f32 v[122:123], v[154:155], v[150:151], v[146:147]
	v_pk_fma_f32 v[124:125], v[156:157], v[152:153], v[148:149]
	v_pk_fma_f32 v[194:195], v[122:123], v[122:123], v[194:195]
	v_pk_fma_f32 v[196:197], v[124:125], v[124:125], v[196:197]
	v_cvt_f32_i32_e32 v118, v118
	v_cvt_f32_i32_e32 v119, v119
	v_cvt_f32_i32_e32 v120, v120
	v_cvt_f32_i32_e32 v121, v121
	v_pk_mul_f32 v[142:143], v[230:231], v[188:189] op_sel_hi:[1,0]
	v_pk_mul_f32 v[144:145], v[232:233], v[188:189] op_sel_hi:[1,0]
	v_pk_fma_f32 v[154:155], v[142:143], v[118:119], v[214:215]
	v_pk_fma_f32 v[156:157], v[144:145], v[120:121], v[216:217]
	v_mul_f32_e32 v154, 0xbfb8aa3b, v154
	v_mul_f32_e32 v155, 0xbfb8aa3b, v155
	v_mul_f32_e32 v156, 0xbfb8aa3b, v156
	v_mul_f32_e32 v157, 0xbfb8aa3b, v157
	v_exp_f32_e32 v154, v154
	v_exp_f32_e32 v155, v155
	v_exp_f32_e32 v156, v156
	v_exp_f32_e32 v157, v157
	v_lshlrev_b32_e32 v146, 16, v174
	v_and_b32_e32 v147, 0xffff0000, v174
	v_lshlrev_b32_e32 v148, 16, v175
	v_and_b32_e32 v149, 0xffff0000, v175
	v_add_f32_e32 v154, 1.0, v154
	v_add_f32_e32 v155, 1.0, v155
	v_add_f32_e32 v156, 1.0, v156
	v_add_f32_e32 v157, 1.0, v157
	v_rcp_f32_e32 v154, v154
	v_rcp_f32_e32 v155, v155
	v_rcp_f32_e32 v156, v156
	v_rcp_f32_e32 v157, v157
	v_lshlrev_b32_e32 v150, 16, v182
	v_and_b32_e32 v151, 0xffff0000, v182
	v_lshlrev_b32_e32 v152, 16, v183
	v_and_b32_e32 v153, 0xffff0000, v183
	v_pk_fma_f32 v[118:119], v[154:155], v[150:151], v[146:147]
	v_pk_fma_f32 v[120:121], v[156:157], v[152:153], v[148:149]
	v_pk_fma_f32 v[194:195], v[118:119], v[118:119], v[194:195]
	v_pk_fma_f32 v[196:197], v[120:121], v[120:121], v[196:197]
	v_cvt_f32_i32_e32 v114, v114
	v_cvt_f32_i32_e32 v115, v115
	v_cvt_f32_i32_e32 v116, v116
	v_cvt_f32_i32_e32 v117, v117
	v_pk_mul_f32 v[142:143], v[234:235], v[188:189] op_sel_hi:[1,0]
	v_pk_mul_f32 v[144:145], v[236:237], v[188:189] op_sel_hi:[1,0]
	v_pk_fma_f32 v[154:155], v[142:143], v[114:115], v[218:219]
	v_pk_fma_f32 v[156:157], v[144:145], v[116:117], v[220:221]
	v_mul_f32_e32 v154, 0xbfb8aa3b, v154
	v_mul_f32_e32 v155, 0xbfb8aa3b, v155
	v_mul_f32_e32 v156, 0xbfb8aa3b, v156
	v_mul_f32_e32 v157, 0xbfb8aa3b, v157
	v_exp_f32_e32 v154, v154
	v_exp_f32_e32 v155, v155
	v_exp_f32_e32 v156, v156
	v_exp_f32_e32 v157, v157
	v_lshlrev_b32_e32 v146, 16, v176
	v_and_b32_e32 v147, 0xffff0000, v176
	v_lshlrev_b32_e32 v148, 16, v177
	v_and_b32_e32 v149, 0xffff0000, v177
	v_add_f32_e32 v154, 1.0, v154
	v_add_f32_e32 v155, 1.0, v155
	v_add_f32_e32 v156, 1.0, v156
	v_add_f32_e32 v157, 1.0, v157
	v_rcp_f32_e32 v154, v154
	v_rcp_f32_e32 v155, v155
	v_rcp_f32_e32 v156, v156
	v_rcp_f32_e32 v157, v157
	v_lshlrev_b32_e32 v150, 16, v184
	v_and_b32_e32 v151, 0xffff0000, v184
	v_lshlrev_b32_e32 v152, 16, v185
	v_and_b32_e32 v153, 0xffff0000, v185
	v_pk_fma_f32 v[114:115], v[154:155], v[150:151], v[146:147]
	v_pk_fma_f32 v[116:117], v[156:157], v[152:153], v[148:149]
	v_pk_fma_f32 v[194:195], v[114:115], v[114:115], v[194:195]
	v_pk_fma_f32 v[196:197], v[116:117], v[116:117], v[196:197]
	v_add_f32_e32 v194, v194, v195
	v_add_f32_e32 v196, v196, v197
	v_add_f32_e32 v194, v194, v196
	ds_bpermute_b32 v195, v58, v194
	s_waitcnt lgkmcnt(0)
	v_add_f32_e32 v194, v194, v195
	ds_bpermute_b32 v195, v59, v194
	s_waitcnt lgkmcnt(0)
	v_add_f32_e32 v194, v194, v195
	s_and_saveexec_b64 s[32:33], s[6:7]
	global_atomic_add_f32 v54, v194, s[70:71] offset:64
	s_or_b64 exec, exec, s[32:33]
	global_load_dword v67, v54, s[68:69] offset:192
	global_load_dwordx4 v[170:173], v56, s[86:87]
	global_load_dwordx4 v[174:177], v56, s[86:87] offset:256
	global_load_dwordx4 v[178:181], v56, s[88:89]
	global_load_dwordx4 v[182:185], v56, s[88:89] offset:256
	s_add_u32 s86, s86, 0xa0000
	s_addc_u32 s87, s87, 0
	s_add_u32 s88, s88, 0xa0000
	s_addc_u32 s89, s89, 0
	s_waitcnt vmcnt(6)
; __device__ __forceinline__ f32x4 acc_i2f(const f32x4 a) { return __builtin_convertvector(__builtin_bit_cast(i32x4, a), f32x4); }
;     __device__ __forceinline__ void operator()(const f32x4 (&acc)[2][2][4][2], const pg8::Unit& u, int wr, int wc, int fr, int fq) const {
;     ...
;                 for (int mm = 0; mm < 2; ++mm) { const int m = 2 * mp + mm, row = row0 + ai * 128 + m * 16; f32x4 ssv = {0.f, 0.f, 0.f, 0.f}; const float sa = (QCLIP / 127.f) * sqrtf(q1v[mm] * (1.f / DM) + EPS);
; #pragma unroll
;                     for (int bj = 0; bj < 2; ++bj) { const size_t off = (size_t)row * DM + col0 + bj * 128;
;                         f32x4 p0, p1, x0, x1; unpack8v(pr[mm][bj], p0, p1); unpack8v(hr[mm][bj], x0, x1);
;                         const f32x4 g0 = acc_i2f(acc[ai][bj][m][0]) * (sb[bj][0] * sa) + bv[bj][0], g1 = acc_i2f(acc[ai][bj][m][1]) * (sb[bj][1] * sa) + bv[bj][1];
;                         const f32x4 h0 = x0 + p0 * sigm4(g0), h1 = x1 + p1 * sigm4(g1);
;                         *(f32x4*)(H + off) = h0; *(f32x4*)(H + off + 4) = h1;
;                         ssv = ssv + h0 * h0; ssv = ssv + h1 * h1; }
;                     float ss = (ssv[0] + ssv[1]) + (ssv[2] + ssv[3]);
;                     ss += __shfl_xor(ss, 16); ss += __shfl_xor(ss, 32);
;                     if (fq == 0) unsafeAtomicAdd(rss3 + row, ss); }
	v_fmamk_f32 v186, v66, 0x39800000, v204
	v_mul_f32_e32 v187, 0x4f800000, v186
	v_cmp_gt_f32_e32 vcc, s67, v186
	s_nop 1
	v_cndmask_b32_e32 v186, v186, v187, vcc
	v_sqrt_f32_e32 v190, v186
	s_nop 0
	v_add_u32_e32 v191, -1, v190
	v_add_u32_e32 v192, 1, v190
	v_fma_f32 v193, -v191, v190, v186
	v_fma_f32 v187, -v192, v190, v186
	v_cmp_ge_f32_e64 s[10:11], 0, v193
	s_nop 1
	v_cndmask_b32_e64 v190, v190, v191, s[10:11]
	v_cmp_lt_f32_e64 s[10:11], 0, v187
	s_nop 1
	v_cndmask_b32_e64 v190, v190, v192, s[10:11]
	v_mul_f32_e32 v191, 0x37800000, v190
	v_cndmask_b32_e32 v190, v190, v191, vcc
	v_cmp_class_f32_e32 vcc, v186, v205
	s_nop 1
	v_cndmask_b32_e32 v186, v190, v186, vcc
	v_mul_f32_e32 v188, 0x3d112245, v186
	v_cvt_f32_i32_e32 v110, v110
	v_cvt_f32_i32_e32 v111, v111
	v_cvt_f32_i32_e32 v112, v112
	v_cvt_f32_i32_e32 v113, v113
	v_pk_mul_f32 v[142:143], v[222:223], v[188:189] op_sel_hi:[1,0]
	v_pk_mul_f32 v[144:145], v[224:225], v[188:189] op_sel_hi:[1,0]
	v_pk_fma_f32 v[154:155], v[142:143], v[110:111], v[206:207]
	v_pk_fma_f32 v[156:157], v[144:145], v[112:113], v[208:209]
	v_mul_f32_e32 v154, 0xbfb8aa3b, v154
	v_mul_f32_e32 v155, 0xbfb8aa3b, v155
	v_mul_f32_e32 v156, 0xbfb8aa3b, v156
	v_mul_f32_e32 v157, 0xbfb8aa3b, v157
	v_exp_f32_e32 v154, v154
	v_exp_f32_e32 v155, v155
	v_exp_f32_e32 v156, v156
	v_exp_f32_e32 v157, v157
	v_lshlrev_b32_e32 v146, 16, v238
	v_and_b32_e32 v147, 0xffff0000, v238
	v_lshlrev_b32_e32 v148, 16, v239
	v_and_b32_e32 v149, 0xffff0000, v239
	v_add_f32_e32 v154, 1.0, v154
	v_add_f32_e32 v155, 1.0, v155
	v_add_f32_e32 v156, 1.0, v156
	v_add_f32_e32 v157, 1.0, v157
	v_rcp_f32_e32 v154, v154
	v_rcp_f32_e32 v155, v155
	v_rcp_f32_e32 v156, v156
	v_rcp_f32_e32 v157, v157
	v_lshlrev_b32_e32 v150, 16, v246
	v_and_b32_e32 v151, 0xffff0000, v246
	v_lshlrev_b32_e32 v152, 16, v247
	v_and_b32_e32 v153, 0xffff0000, v247
	v_pk_fma_f32 v[110:111], v[154:155], v[150:151], v[146:147]
	v_pk_fma_f32 v[112:113], v[156:157], v[152:153], v[148:149]
	v_pk_mul_f32 v[194:195], v[110:111], v[110:111]
	v_pk_mul_f32 v[196:197], v[112:113], v[112:113]
	v_cvt_f32_i32_e32 v106, v106
	v_cvt_f32_i32_e32 v107, v107
	v_cvt_f32_i32_e32 v108, v108
	v_cvt_f32_i32_e32 v109, v109
	v_pk_mul_f32 v[142:143], v[226:227], v[188:189] op_sel_hi:[1,0]
	v_pk_mul_f32 v[144:145], v[228:229], v[188:189] op_sel_hi:[1,0]
	v_pk_fma_f32 v[154:155], v[142:143], v[106:107], v[210:211]
	v_pk_fma_f32 v[156:157], v[144:145], v[108:109], v[212:213]
	v_mul_f32_e32 v154, 0xbfb8aa3b, v154
	v_mul_f32_e32 v155, 0xbfb8aa3b, v155
	v_mul_f32_e32 v156, 0xbfb8aa3b, v156
	v_mul_f32_e32 v157, 0xbfb8aa3b, v157
	v_exp_f32_e32 v154, v154
	v_exp_f32_e32 v155, v155
	v_exp_f32_e32 v156, v156
	v_exp_f32_e32 v157, v157
	v_lshlrev_b32_e32 v146, 16, v240
	v_and_b32_e32 v147, 0xffff0000, v240
	v_lshlrev_b32_e32 v148, 16, v241
	v_and_b32_e32 v149, 0xffff0000, v241
	v_add_f32_e32 v154, 1.0, v154
	v_add_f32_e32 v155, 1.0, v155
	v_add_f32_e32 v156, 1.0, v156
	v_add_f32_e32 v157, 1.0, v157
	v_rcp_f32_e32 v154, v154
	v_rcp_f32_e32 v155, v155
	v_rcp_f32_e32 v156, v156
	v_rcp_f32_e32 v157, v157
	v_lshlrev_b32_e32 v150, 16, v248
	v_and_b32_e32 v151, 0xffff0000, v248
	v_lshlrev_b32_e32 v152, 16, v249
	v_and_b32_e32 v153, 0xffff0000, v249
	v_pk_fma_f32 v[106:107], v[154:155], v[150:151], v[146:147]
	v_pk_fma_f32 v[108:109], v[156:157], v[152:153], v[148:149]
	v_pk_fma_f32 v[194:195], v[106:107], v[106:107], v[194:195]
	v_pk_fma_f32 v[196:197], v[108:109], v[108:109], v[196:197]
	v_cvt_f32_i32_e32 v102, v102
	v_cvt_f32_i32_e32 v103, v103
	v_cvt_f32_i32_e32 v104, v104
	v_cvt_f32_i32_e32 v105, v105
	v_pk_mul_f32 v[142:143], v[230:231], v[188:189] op_sel_hi:[1,0]
	v_pk_mul_f32 v[144:145], v[232:233], v[188:189] op_sel_hi:[1,0]
	v_pk_fma_f32 v[154:155], v[142:143], v[102:103], v[214:215]
	v_pk_fma_f32 v[156:157], v[144:145], v[104:105], v[216:217]
	v_mul_f32_e32 v154, 0xbfb8aa3b, v154
	v_mul_f32_e32 v155, 0xbfb8aa3b, v155
	v_mul_f32_e32 v156, 0xbfb8aa3b, v156
	v_mul_f32_e32 v157, 0xbfb8aa3b, v157
	v_exp_f32_e32 v154, v154
	v_exp_f32_e32 v155, v155
	v_exp_f32_e32 v156, v156
	v_exp_f32_e32 v157, v157
	v_lshlrev_b32_e32 v146, 16, v242
	v_and_b32_e32 v147, 0xffff0000, v242
	v_lshlrev_b32_e32 v148, 16, v243
	v_and_b32_e32 v149, 0xffff0000, v243
	v_add_f32_e32 v154, 1.0, v154
	v_add_f32_e32 v155, 1.0, v155
	v_add_f32_e32 v156, 1.0, v156
	v_add_f32_e32 v157, 1.0, v157
	v_rcp_f32_e32 v154, v154
	v_rcp_f32_e32 v155, v155
	v_rcp_f32_e32 v156, v156
	v_rcp_f32_e32 v157, v157
	v_lshlrev_b32_e32 v150, 16, v250
	v_and_b32_e32 v151, 0xffff0000, v250
	v_lshlrev_b32_e32 v152, 16, v251
	v_and_b32_e32 v153, 0xffff0000, v251
	v_pk_fma_f32 v[102:103], v[154:155], v[150:151], v[146:147]
	v_pk_fma_f32 v[104:105], v[156:157], v[152:153], v[148:149]
	v_pk_fma_f32 v[194:195], v[102:103], v[102:103], v[194:195]
	v_pk_fma_f32 v[196:197], v[104:105], v[104:105], v[196:197]
	v_cvt_f32_i32_e32 v98, v98
	v_cvt_f32_i32_e32 v99, v99
	v_cvt_f32_i32_e32 v100, v100
	v_cvt_f32_i32_e32 v101, v101
	v_pk_mul_f32 v[142:143], v[234:235], v[188:189] op_sel_hi:[1,0]
	v_pk_mul_f32 v[144:145], v[236:237], v[188:189] op_sel_hi:[1,0]
	v_pk_fma_f32 v[154:155], v[142:143], v[98:99], v[218:219]
	v_pk_fma_f32 v[156:157], v[144:145], v[100:101], v[220:221]
	v_mul_f32_e32 v154, 0xbfb8aa3b, v154
	v_mul_f32_e32 v155, 0xbfb8aa3b, v155
	v_mul_f32_e32 v156, 0xbfb8aa3b, v156
	v_mul_f32_e32 v157, 0xbfb8aa3b, v157
	v_exp_f32_e32 v154, v154
	v_exp_f32_e32 v155, v155
	v_exp_f32_e32 v156, v156
	v_exp_f32_e32 v157, v157
	v_lshlrev_b32_e32 v146, 16, v244
	v_and_b32_e32 v147, 0xffff0000, v244
	v_lshlrev_b32_e32 v148, 16, v245
	v_and_b32_e32 v149, 0xffff0000, v245
	v_add_f32_e32 v154, 1.0, v154
	v_add_f32_e32 v155, 1.0, v155
	v_add_f32_e32 v156, 1.0, v156
	v_add_f32_e32 v157, 1.0, v157
	v_rcp_f32_e32 v154, v154
	v_rcp_f32_e32 v155, v155
	v_rcp_f32_e32 v156, v156
	v_rcp_f32_e32 v157, v157
	v_lshlrev_b32_e32 v150, 16, v252
	v_and_b32_e32 v151, 0xffff0000, v252
	v_lshlrev_b32_e32 v152, 16, v253
	v_and_b32_e32 v153, 0xffff0000, v253
	v_pk_fma_f32 v[98:99], v[154:155], v[150:151], v[146:147]
	v_pk_fma_f32 v[100:101], v[156:157], v[152:153], v[148:149]
	v_pk_fma_f32 v[194:195], v[98:99], v[98:99], v[194:195]
	v_pk_fma_f32 v[196:197], v[100:101], v[100:101], v[196:197]
	v_add_f32_e32 v194, v194, v195
	v_add_f32_e32 v196, v196, v197
	v_add_f32_e32 v194, v194, v196
	ds_bpermute_b32 v195, v58, v194
	s_waitcnt lgkmcnt(0)
; __device__ __forceinline__ f32x4 acc_i2f(const f32x4 a) { return __builtin_convertvector(__builtin_bit_cast(i32x4, a), f32x4); }
;     __device__ __forceinline__ void operator()(const f32x4 (&acc)[2][2][4][2], const pg8::Unit& u, int wr, int wc, int fr, int fq) const {
;     ...
;                 for (int mm = 0; mm < 2; ++mm) { const int m = 2 * mp + mm, row = row0 + ai * 128 + m * 16; f32x4 ssv = {0.f, 0.f, 0.f, 0.f}; const float sa = (QCLIP / 127.f) * sqrtf(q1v[mm] * (1.f / DM) + EPS);
; #pragma unroll
;                     for (int bj = 0; bj < 2; ++bj) { const size_t off = (size_t)row * DM + col0 + bj * 128;
;                         f32x4 p0, p1, x0, x1; unpack8v(pr[mm][bj], p0, p1); unpack8v(hr[mm][bj], x0, x1);
;                         const f32x4 g0 = acc_i2f(acc[ai][bj][m][0]) * (sb[bj][0] * sa) + bv[bj][0], g1 = acc_i2f(acc[ai][bj][m][1]) * (sb[bj][1] * sa) + bv[bj][1];
;                         const f32x4 h0 = x0 + p0 * sigm4(g0), h1 = x1 + p1 * sigm4(g1);
;                         *(f32x4*)(H + off) = h0; *(f32x4*)(H + off + 4) = h1;
;                         ssv = ssv + h0 * h0; ssv = ssv + h1 * h1; }
;                     float ss = (ssv[0] + ssv[1]) + (ssv[2] + ssv[3]);
;                     ss += __shfl_xor(ss, 16); ss += __shfl_xor(ss, 32);
;                     if (fq == 0) unsafeAtomicAdd(rss3 + row, ss); }
	v_add_f32_e32 v194, v194, v195
	ds_bpermute_b32 v195, v59, v194
	s_waitcnt lgkmcnt(0)
	v_add_f32_e32 v194, v194, v195
	s_and_saveexec_b64 s[32:33], s[6:7]
	global_atomic_add_f32 v54, v194, s[70:71] offset:128
	s_or_b64 exec, exec, s[32:33]
	global_load_dword v66, v54, s[68:69] offset:512
	global_load_dwordx4 v[238:241], v56, s[86:87]
	global_load_dwordx4 v[242:245], v56, s[86:87] offset:256
	global_load_dwordx4 v[246:249], v56, s[88:89]
	global_load_dwordx4 v[250:253], v56, s[88:89] offset:256
	s_add_u32 s86, s86, 0x20000
	s_addc_u32 s87, s87, 0
	s_add_u32 s88, s88, 0x20000
	s_addc_u32 s89, s89, 0
	s_waitcnt vmcnt(6)
	v_fmamk_f32 v186, v67, 0x39800000, v204
	v_mul_f32_e32 v187, 0x4f800000, v186
	v_cmp_gt_f32_e32 vcc, s67, v186
	s_nop 1
	v_cndmask_b32_e32 v186, v186, v187, vcc
	v_sqrt_f32_e32 v190, v186
	s_nop 0
	v_add_u32_e32 v191, -1, v190
	v_add_u32_e32 v192, 1, v190
	v_fma_f32 v193, -v191, v190, v186
	v_fma_f32 v187, -v192, v190, v186
	v_cmp_ge_f32_e64 s[10:11], 0, v193
	s_nop 1
	v_cndmask_b32_e64 v190, v190, v191, s[10:11]
	v_cmp_lt_f32_e64 s[10:11], 0, v187
	s_nop 1
	v_cndmask_b32_e64 v190, v190, v192, s[10:11]
	v_mul_f32_e32 v191, 0x37800000, v190
	v_cndmask_b32_e32 v190, v190, v191, vcc
	v_cmp_class_f32_e32 vcc, v186, v205
	s_nop 1
	v_cndmask_b32_e32 v186, v190, v186, vcc
	v_mul_f32_e32 v188, 0x3d112245, v186
	v_cvt_f32_i32_e32 v94, v94
	v_cvt_f32_i32_e32 v95, v95
	v_cvt_f32_i32_e32 v96, v96
	v_cvt_f32_i32_e32 v97, v97
	v_pk_mul_f32 v[142:143], v[222:223], v[188:189] op_sel_hi:[1,0]
	v_pk_mul_f32 v[144:145], v[224:225], v[188:189] op_sel_hi:[1,0]
	v_pk_fma_f32 v[154:155], v[142:143], v[94:95], v[206:207]
	v_pk_fma_f32 v[156:157], v[144:145], v[96:97], v[208:209]
	v_mul_f32_e32 v154, 0xbfb8aa3b, v154
	v_mul_f32_e32 v155, 0xbfb8aa3b, v155
	v_mul_f32_e32 v156, 0xbfb8aa3b, v156
	v_mul_f32_e32 v157, 0xbfb8aa3b, v157
	v_exp_f32_e32 v154, v154
	v_exp_f32_e32 v155, v155
	v_exp_f32_e32 v156, v156
	v_exp_f32_e32 v157, v157
	v_lshlrev_b32_e32 v146, 16, v170
	v_and_b32_e32 v147, 0xffff0000, v170
	v_lshlrev_b32_e32 v148, 16, v171
	v_and_b32_e32 v149, 0xffff0000, v171
	v_add_f32_e32 v154, 1.0, v154
	v_add_f32_e32 v155, 1.0, v155
	v_add_f32_e32 v156, 1.0, v156
	v_add_f32_e32 v157, 1.0, v157
	v_rcp_f32_e32 v154, v154
	v_rcp_f32_e32 v155, v155
	v_rcp_f32_e32 v156, v156
	v_rcp_f32_e32 v157, v157
	v_lshlrev_b32_e32 v150, 16, v178
	v_and_b32_e32 v151, 0xffff0000, v178
	v_lshlrev_b32_e32 v152, 16, v179
	v_and_b32_e32 v153, 0xffff0000, v179
	v_pk_fma_f32 v[94:95], v[154:155], v[150:151], v[146:147]
	v_pk_fma_f32 v[96:97], v[156:157], v[152:153], v[148:149]
	v_pk_mul_f32 v[194:195], v[94:95], v[94:95]
	v_pk_mul_f32 v[196:197], v[96:97], v[96:97]
	v_cvt_f32_i32_e32 v90, v90
	v_cvt_f32_i32_e32 v91, v91
	v_cvt_f32_i32_e32 v92, v92
	v_cvt_f32_i32_e32 v93, v93
	v_pk_mul_f32 v[142:143], v[226:227], v[188:189] op_sel_hi:[1,0]
	v_pk_mul_f32 v[144:145], v[228:229], v[188:189] op_sel_hi:[1,0]
	v_pk_fma_f32 v[154:155], v[142:143], v[90:91], v[210:211]
	v_pk_fma_f32 v[156:157], v[144:145], v[92:93], v[212:213]
	v_mul_f32_e32 v154, 0xbfb8aa3b, v154
	v_mul_f32_e32 v155, 0xbfb8aa3b, v155
	v_mul_f32_e32 v156, 0xbfb8aa3b, v156
	v_mul_f32_e32 v157, 0xbfb8aa3b, v157
	v_exp_f32_e32 v154, v154
	v_exp_f32_e32 v155, v155
	v_exp_f32_e32 v156, v156
	v_exp_f32_e32 v157, v157
	v_lshlrev_b32_e32 v146, 16, v172
	v_and_b32_e32 v147, 0xffff0000, v172
	v_lshlrev_b32_e32 v148, 16, v173
	v_and_b32_e32 v149, 0xffff0000, v173
	v_add_f32_e32 v154, 1.0, v154
	v_add_f32_e32 v155, 1.0, v155
	v_add_f32_e32 v156, 1.0, v156
	v_add_f32_e32 v157, 1.0, v157
	v_rcp_f32_e32 v154, v154
	v_rcp_f32_e32 v155, v155
	v_rcp_f32_e32 v156, v156
	v_rcp_f32_e32 v157, v157
	v_lshlrev_b32_e32 v150, 16, v180
	v_and_b32_e32 v151, 0xffff0000, v180
	v_lshlrev_b32_e32 v152, 16, v181
	v_and_b32_e32 v153, 0xffff0000, v181
	v_pk_fma_f32 v[90:91], v[154:155], v[150:151], v[146:147]
	v_pk_fma_f32 v[92:93], v[156:157], v[152:153], v[148:149]
	v_pk_fma_f32 v[194:195], v[90:91], v[90:91], v[194:195]
	v_pk_fma_f32 v[196:197], v[92:93], v[92:93], v[196:197]
	v_cvt_f32_i32_e32 v86, v86
	v_cvt_f32_i32_e32 v87, v87
	v_cvt_f32_i32_e32 v88, v88
	v_cvt_f32_i32_e32 v89, v89
	v_pk_mul_f32 v[142:143], v[230:231], v[188:189] op_sel_hi:[1,0]
	v_pk_mul_f32 v[144:145], v[232:233], v[188:189] op_sel_hi:[1,0]
	v_pk_fma_f32 v[154:155], v[142:143], v[86:87], v[214:215]
	v_pk_fma_f32 v[156:157], v[144:145], v[88:89], v[216:217]
	v_mul_f32_e32 v154, 0xbfb8aa3b, v154
	v_mul_f32_e32 v155, 0xbfb8aa3b, v155
	v_mul_f32_e32 v156, 0xbfb8aa3b, v156
	v_mul_f32_e32 v157, 0xbfb8aa3b, v157
	v_exp_f32_e32 v154, v154
	v_exp_f32_e32 v155, v155
	v_exp_f32_e32 v156, v156
	v_exp_f32_e32 v157, v157
	v_lshlrev_b32_e32 v146, 16, v174
	v_and_b32_e32 v147, 0xffff0000, v174
	v_lshlrev_b32_e32 v148, 16, v175
	v_and_b32_e32 v149, 0xffff0000, v175
	v_add_f32_e32 v154, 1.0, v154
	v_add_f32_e32 v155, 1.0, v155
	v_add_f32_e32 v156, 1.0, v156
	v_add_f32_e32 v157, 1.0, v157
	v_rcp_f32_e32 v154, v154
	v_rcp_f32_e32 v155, v155
	v_rcp_f32_e32 v156, v156
	v_rcp_f32_e32 v157, v157
	v_lshlrev_b32_e32 v150, 16, v182
	v_and_b32_e32 v151, 0xffff0000, v182
	v_lshlrev_b32_e32 v152, 16, v183
	v_and_b32_e32 v153, 0xffff0000, v183
	v_pk_fma_f32 v[86:87], v[154:155], v[150:151], v[146:147]
	v_pk_fma_f32 v[88:89], v[156:157], v[152:153], v[148:149]
	v_pk_fma_f32 v[194:195], v[86:87], v[86:87], v[194:195]
	v_pk_fma_f32 v[196:197], v[88:89], v[88:89], v[196:197]
	v_cvt_f32_i32_e32 v82, v82
	v_cvt_f32_i32_e32 v83, v83
	v_cvt_f32_i32_e32 v84, v84
	v_cvt_f32_i32_e32 v85, v85
	v_pk_mul_f32 v[142:143], v[234:235], v[188:189] op_sel_hi:[1,0]
	v_pk_mul_f32 v[144:145], v[236:237], v[188:189] op_sel_hi:[1,0]
	v_pk_fma_f32 v[154:155], v[142:143], v[82:83], v[218:219]
	v_pk_fma_f32 v[156:157], v[144:145], v[84:85], v[220:221]
	v_mul_f32_e32 v154, 0xbfb8aa3b, v154
	v_mul_f32_e32 v155, 0xbfb8aa3b, v155
	v_mul_f32_e32 v156, 0xbfb8aa3b, v156
	v_mul_f32_e32 v157, 0xbfb8aa3b, v157
	v_exp_f32_e32 v154, v154
	v_exp_f32_e32 v155, v155
	v_exp_f32_e32 v156, v156
	v_exp_f32_e32 v157, v157
	v_lshlrev_b32_e32 v146, 16, v176
	v_and_b32_e32 v147, 0xffff0000, v176
	v_lshlrev_b32_e32 v148, 16, v177
	v_and_b32_e32 v149, 0xffff0000, v177
	v_add_f32_e32 v154, 1.0, v154
	v_add_f32_e32 v155, 1.0, v155
	v_add_f32_e32 v156, 1.0, v156
	v_add_f32_e32 v157, 1.0, v157
	v_rcp_f32_e32 v154, v154
	v_rcp_f32_e32 v155, v155
	v_rcp_f32_e32 v156, v156
	v_rcp_f32_e32 v157, v157
	v_lshlrev_b32_e32 v150, 16, v184
	v_and_b32_e32 v151, 0xffff0000, v184
	v_lshlrev_b32_e32 v152, 16, v185
	v_and_b32_e32 v153, 0xffff0000, v185
	v_pk_fma_f32 v[82:83], v[154:155], v[150:151], v[146:147]
	v_pk_fma_f32 v[84:85], v[156:157], v[152:153], v[148:149]
	v_pk_fma_f32 v[194:195], v[82:83], v[82:83], v[194:195]
	v_pk_fma_f32 v[196:197], v[84:85], v[84:85], v[196:197]
	v_add_f32_e32 v194, v194, v195
	v_add_f32_e32 v196, v196, v197
	v_add_f32_e32 v194, v194, v196
	ds_bpermute_b32 v195, v58, v194
	s_waitcnt lgkmcnt(0)
; __device__ __forceinline__ f32x4 acc_i2f(const f32x4 a) { return __builtin_convertvector(__builtin_bit_cast(i32x4, a), f32x4); }
;     __device__ __forceinline__ void operator()(const f32x4 (&acc)[2][2][4][2], const pg8::Unit& u, int wr, int wc, int fr, int fq) const {
;     ...
;                 for (int mm = 0; mm < 2; ++mm) { const int m = 2 * mp + mm, row = row0 + ai * 128 + m * 16; f32x4 ssv = {0.f, 0.f, 0.f, 0.f}; const float sa = (QCLIP / 127.f) * sqrtf(q1v[mm] * (1.f / DM) + EPS);
; #pragma unroll
;                     for (int bj = 0; bj < 2; ++bj) { const size_t off = (size_t)row * DM + col0 + bj * 128;
;                         f32x4 p0, p1, x0, x1; unpack8v(pr[mm][bj], p0, p1); unpack8v(hr[mm][bj], x0, x1);
;                         const f32x4 g0 = acc_i2f(acc[ai][bj][m][0]) * (sb[bj][0] * sa) + bv[bj][0], g1 = acc_i2f(acc[ai][bj][m][1]) * (sb[bj][1] * sa) + bv[bj][1];
;                         const f32x4 h0 = x0 + p0 * sigm4(g0), h1 = x1 + p1 * sigm4(g1);
;                         *(f32x4*)(H + off) = h0; *(f32x4*)(H + off + 4) = h1;
;                         ssv = ssv + h0 * h0; ssv = ssv + h1 * h1; }
;                     float ss = (ssv[0] + ssv[1]) + (ssv[2] + ssv[3]);
;                     ss += __shfl_xor(ss, 16); ss += __shfl_xor(ss, 32);
;                     if (fq == 0) unsafeAtomicAdd(rss3 + row, ss); }
	v_add_f32_e32 v194, v194, v195
	ds_bpermute_b32 v195, v59, v194
	s_waitcnt lgkmcnt(0)
	v_add_f32_e32 v194, v194, v195
	s_and_saveexec_b64 s[32:33], s[6:7]
	global_atomic_add_f32 v54, v194, s[70:71] offset:192
	s_or_b64 exec, exec, s[32:33]
	global_load_dword v67, v54, s[68:69] offset:576
	global_load_dwordx4 v[170:173], v56, s[86:87]
	global_load_dwordx4 v[174:177], v56, s[86:87] offset:256
	global_load_dwordx4 v[178:181], v56, s[88:89]
	global_load_dwordx4 v[182:185], v56, s[88:89] offset:256
	s_add_u32 s86, s86, 0x20000
	s_addc_u32 s87, s87, 0
	s_add_u32 s88, s88, 0x20000
	s_addc_u32 s89, s89, 0
	s_waitcnt vmcnt(6)
	v_fmamk_f32 v186, v66, 0x39800000, v204
	v_mul_f32_e32 v187, 0x4f800000, v186
	v_cmp_gt_f32_e32 vcc, s67, v186
	s_nop 1
	v_cndmask_b32_e32 v186, v186, v187, vcc
	v_sqrt_f32_e32 v190, v186
	s_nop 0
	v_add_u32_e32 v191, -1, v190
	v_add_u32_e32 v192, 1, v190
	v_fma_f32 v193, -v191, v190, v186
	v_fma_f32 v187, -v192, v190, v186
	v_cmp_ge_f32_e64 s[10:11], 0, v193
	s_nop 1
	v_cndmask_b32_e64 v190, v190, v191, s[10:11]
	v_cmp_lt_f32_e64 s[10:11], 0, v187
	s_nop 1
	v_cndmask_b32_e64 v190, v190, v192, s[10:11]
	v_mul_f32_e32 v191, 0x37800000, v190
	v_cndmask_b32_e32 v190, v190, v191, vcc
	v_cmp_class_f32_e32 vcc, v186, v205
	s_nop 1
	v_cndmask_b32_e32 v186, v190, v186, vcc
	v_mul_f32_e32 v188, 0x3d112245, v186
	v_cvt_f32_i32_e32 v78, v78
	v_cvt_f32_i32_e32 v79, v79
	v_cvt_f32_i32_e32 v80, v80
	v_cvt_f32_i32_e32 v81, v81
	v_pk_mul_f32 v[142:143], v[222:223], v[188:189] op_sel_hi:[1,0]
	v_pk_mul_f32 v[144:145], v[224:225], v[188:189] op_sel_hi:[1,0]
	v_pk_fma_f32 v[154:155], v[142:143], v[78:79], v[206:207]
	v_pk_fma_f32 v[156:157], v[144:145], v[80:81], v[208:209]
	v_mul_f32_e32 v154, 0xbfb8aa3b, v154
	v_mul_f32_e32 v155, 0xbfb8aa3b, v155
	v_mul_f32_e32 v156, 0xbfb8aa3b, v156
	v_mul_f32_e32 v157, 0xbfb8aa3b, v157
	v_exp_f32_e32 v154, v154
	v_exp_f32_e32 v155, v155
	v_exp_f32_e32 v156, v156
	v_exp_f32_e32 v157, v157
	v_lshlrev_b32_e32 v146, 16, v238
	v_and_b32_e32 v147, 0xffff0000, v238
	v_lshlrev_b32_e32 v148, 16, v239
	v_and_b32_e32 v149, 0xffff0000, v239
	v_add_f32_e32 v154, 1.0, v154
	v_add_f32_e32 v155, 1.0, v155
	v_add_f32_e32 v156, 1.0, v156
	v_add_f32_e32 v157, 1.0, v157
	v_rcp_f32_e32 v154, v154
	v_rcp_f32_e32 v155, v155
	v_rcp_f32_e32 v156, v156
	v_rcp_f32_e32 v157, v157
	v_lshlrev_b32_e32 v150, 16, v246
	v_and_b32_e32 v151, 0xffff0000, v246
	v_lshlrev_b32_e32 v152, 16, v247
	v_and_b32_e32 v153, 0xffff0000, v247
	v_pk_fma_f32 v[78:79], v[154:155], v[150:151], v[146:147]
	v_pk_fma_f32 v[80:81], v[156:157], v[152:153], v[148:149]
	v_pk_mul_f32 v[194:195], v[78:79], v[78:79]
	v_pk_mul_f32 v[196:197], v[80:81], v[80:81]
	v_cvt_f32_i32_e32 v74, v74
	v_cvt_f32_i32_e32 v75, v75
	v_cvt_f32_i32_e32 v76, v76
	v_cvt_f32_i32_e32 v77, v77
	v_pk_mul_f32 v[142:143], v[226:227], v[188:189] op_sel_hi:[1,0]
	v_pk_mul_f32 v[144:145], v[228:229], v[188:189] op_sel_hi:[1,0]
	v_pk_fma_f32 v[154:155], v[142:143], v[74:75], v[210:211]
	v_pk_fma_f32 v[156:157], v[144:145], v[76:77], v[212:213]
	v_mul_f32_e32 v154, 0xbfb8aa3b, v154
	v_mul_f32_e32 v155, 0xbfb8aa3b, v155
	v_mul_f32_e32 v156, 0xbfb8aa3b, v156
	v_mul_f32_e32 v157, 0xbfb8aa3b, v157
	v_exp_f32_e32 v154, v154
	v_exp_f32_e32 v155, v155
	v_exp_f32_e32 v156, v156
	v_exp_f32_e32 v157, v157
	v_lshlrev_b32_e32 v146, 16, v240
	v_and_b32_e32 v147, 0xffff0000, v240
	v_lshlrev_b32_e32 v148, 16, v241
	v_and_b32_e32 v149, 0xffff0000, v241
	v_add_f32_e32 v154, 1.0, v154
	v_add_f32_e32 v155, 1.0, v155
	v_add_f32_e32 v156, 1.0, v156
	v_add_f32_e32 v157, 1.0, v157
	v_rcp_f32_e32 v154, v154
	v_rcp_f32_e32 v155, v155
	v_rcp_f32_e32 v156, v156
	v_rcp_f32_e32 v157, v157
	v_lshlrev_b32_e32 v150, 16, v248
	v_and_b32_e32 v151, 0xffff0000, v248
	v_lshlrev_b32_e32 v152, 16, v249
	v_and_b32_e32 v153, 0xffff0000, v249
	v_pk_fma_f32 v[74:75], v[154:155], v[150:151], v[146:147]
	v_pk_fma_f32 v[76:77], v[156:157], v[152:153], v[148:149]
	v_pk_fma_f32 v[194:195], v[74:75], v[74:75], v[194:195]
	v_pk_fma_f32 v[196:197], v[76:77], v[76:77], v[196:197]
	v_cvt_f32_i32_e32 v70, v70
	v_cvt_f32_i32_e32 v71, v71
	v_cvt_f32_i32_e32 v72, v72
	v_cvt_f32_i32_e32 v73, v73
	v_pk_mul_f32 v[142:143], v[230:231], v[188:189] op_sel_hi:[1,0]
	v_pk_mul_f32 v[144:145], v[232:233], v[188:189] op_sel_hi:[1,0]
	v_pk_fma_f32 v[154:155], v[142:143], v[70:71], v[214:215]
	v_pk_fma_f32 v[156:157], v[144:145], v[72:73], v[216:217]
	v_mul_f32_e32 v154, 0xbfb8aa3b, v154
	v_mul_f32_e32 v155, 0xbfb8aa3b, v155
	v_mul_f32_e32 v156, 0xbfb8aa3b, v156
	v_mul_f32_e32 v157, 0xbfb8aa3b, v157
	v_exp_f32_e32 v154, v154
	v_exp_f32_e32 v155, v155
	v_exp_f32_e32 v156, v156
	v_exp_f32_e32 v157, v157
	v_lshlrev_b32_e32 v146, 16, v242
	v_and_b32_e32 v147, 0xffff0000, v242
	v_lshlrev_b32_e32 v148, 16, v243
	v_and_b32_e32 v149, 0xffff0000, v243
	v_add_f32_e32 v154, 1.0, v154
	v_add_f32_e32 v155, 1.0, v155
	v_add_f32_e32 v156, 1.0, v156
	v_add_f32_e32 v157, 1.0, v157
	v_rcp_f32_e32 v154, v154
	v_rcp_f32_e32 v155, v155
	v_rcp_f32_e32 v156, v156
	v_rcp_f32_e32 v157, v157
	v_lshlrev_b32_e32 v150, 16, v250
	v_and_b32_e32 v151, 0xffff0000, v250
	v_lshlrev_b32_e32 v152, 16, v251
	v_and_b32_e32 v153, 0xffff0000, v251
	v_pk_fma_f32 v[70:71], v[154:155], v[150:151], v[146:147]
	v_pk_fma_f32 v[72:73], v[156:157], v[152:153], v[148:149]
	v_pk_fma_f32 v[194:195], v[70:71], v[70:71], v[194:195]
	v_pk_fma_f32 v[196:197], v[72:73], v[72:73], v[196:197]
	v_cvt_f32_i32_e32 v62, v62
	v_cvt_f32_i32_e32 v63, v63
	v_cvt_f32_i32_e32 v64, v64
	v_cvt_f32_i32_e32 v65, v65
	v_pk_mul_f32 v[142:143], v[234:235], v[188:189] op_sel_hi:[1,0]
	v_pk_mul_f32 v[144:145], v[236:237], v[188:189] op_sel_hi:[1,0]
	v_pk_fma_f32 v[154:155], v[142:143], v[62:63], v[218:219]
	v_pk_fma_f32 v[156:157], v[144:145], v[64:65], v[220:221]
	v_mul_f32_e32 v154, 0xbfb8aa3b, v154
	v_mul_f32_e32 v155, 0xbfb8aa3b, v155
	v_mul_f32_e32 v156, 0xbfb8aa3b, v156
	v_mul_f32_e32 v157, 0xbfb8aa3b, v157
	v_exp_f32_e32 v154, v154
	v_exp_f32_e32 v155, v155
	v_exp_f32_e32 v156, v156
	v_exp_f32_e32 v157, v157
	v_lshlrev_b32_e32 v146, 16, v244
	v_and_b32_e32 v147, 0xffff0000, v244
	v_lshlrev_b32_e32 v148, 16, v245
	v_and_b32_e32 v149, 0xffff0000, v245
	v_add_f32_e32 v154, 1.0, v154
	v_add_f32_e32 v155, 1.0, v155
	v_add_f32_e32 v156, 1.0, v156
	v_add_f32_e32 v157, 1.0, v157
	v_rcp_f32_e32 v154, v154
	v_rcp_f32_e32 v155, v155
	v_rcp_f32_e32 v156, v156
	v_rcp_f32_e32 v157, v157
	v_lshlrev_b32_e32 v150, 16, v252
	v_and_b32_e32 v151, 0xffff0000, v252
	v_lshlrev_b32_e32 v152, 16, v253
	v_and_b32_e32 v153, 0xffff0000, v253
	v_pk_fma_f32 v[62:63], v[154:155], v[150:151], v[146:147]
	v_pk_fma_f32 v[64:65], v[156:157], v[152:153], v[148:149]
	v_pk_fma_f32 v[194:195], v[62:63], v[62:63], v[194:195]
	v_pk_fma_f32 v[196:197], v[64:65], v[64:65], v[196:197]
	v_add_f32_e32 v194, v194, v195
	v_add_f32_e32 v196, v196, v197
	v_add_f32_e32 v194, v194, v196
	ds_bpermute_b32 v195, v58, v194
	s_waitcnt lgkmcnt(0)
; __device__ __forceinline__ f32x4 acc_i2f(const f32x4 a) { return __builtin_convertvector(__builtin_bit_cast(i32x4, a), f32x4); }
;     __device__ __forceinline__ void operator()(const f32x4 (&acc)[2][2][4][2], const pg8::Unit& u, int wr, int wc, int fr, int fq) const {
;     ...
;                 for (int mm = 0; mm < 2; ++mm) { const int m = 2 * mp + mm, row = row0 + ai * 128 + m * 16; f32x4 ssv = {0.f, 0.f, 0.f, 0.f}; const float sa = (QCLIP / 127.f) * sqrtf(q1v[mm] * (1.f / DM) + EPS);
; #pragma unroll
;                     for (int bj = 0; bj < 2; ++bj) { const size_t off = (size_t)row * DM + col0 + bj * 128;
;                         f32x4 p0, p1, x0, x1; unpack8v(pr[mm][bj], p0, p1); unpack8v(hr[mm][bj], x0, x1);
;                         const f32x4 g0 = acc_i2f(acc[ai][bj][m][0]) * (sb[bj][0] * sa) + bv[bj][0], g1 = acc_i2f(acc[ai][bj][m][1]) * (sb[bj][1] * sa) + bv[bj][1];
;                         const f32x4 h0 = x0 + p0 * sigm4(g0), h1 = x1 + p1 * sigm4(g1);
;                         *(f32x4*)(H + off) = h0; *(f32x4*)(H + off + 4) = h1;
;                         ssv = ssv + h0 * h0; ssv = ssv + h1 * h1; }
;                     float ss = (ssv[0] + ssv[1]) + (ssv[2] + ssv[3]);
;                     ss += __shfl_xor(ss, 16); ss += __shfl_xor(ss, 32);
;                     if (fq == 0) unsafeAtomicAdd(rss3 + row, ss); }
	v_add_f32_e32 v194, v194, v195
	ds_bpermute_b32 v195, v59, v194
	s_waitcnt lgkmcnt(0)
	v_add_f32_e32 v194, v194, v195
	s_and_saveexec_b64 s[32:33], s[6:7]
	global_atomic_add_f32 v54, v194, s[70:71] offset:512
	s_or_b64 exec, exec, s[32:33]
	global_load_dword v66, v54, s[68:69] offset:640
	global_load_dwordx4 v[238:241], v56, s[86:87]
	global_load_dwordx4 v[242:245], v56, s[86:87] offset:256
	global_load_dwordx4 v[246:249], v56, s[88:89]
	global_load_dwordx4 v[250:253], v56, s[88:89] offset:256
	s_add_u32 s86, s86, 0x20000
	s_addc_u32 s87, s87, 0
	s_add_u32 s88, s88, 0x20000
	s_addc_u32 s89, s89, 0
	s_waitcnt vmcnt(6)
	v_fmamk_f32 v186, v67, 0x39800000, v204
	v_mul_f32_e32 v187, 0x4f800000, v186
	v_cmp_gt_f32_e32 vcc, s67, v186
	s_nop 1
	v_cndmask_b32_e32 v186, v186, v187, vcc
	v_sqrt_f32_e32 v190, v186
	s_nop 0
	v_add_u32_e32 v191, -1, v190
	v_add_u32_e32 v192, 1, v190
	v_fma_f32 v193, -v191, v190, v186
	v_fma_f32 v187, -v192, v190, v186
	v_cmp_ge_f32_e64 s[10:11], 0, v193
	s_nop 1
	v_cndmask_b32_e64 v190, v190, v191, s[10:11]
	v_cmp_lt_f32_e64 s[10:11], 0, v187
	s_nop 1
	v_cndmask_b32_e64 v190, v190, v192, s[10:11]
	v_mul_f32_e32 v191, 0x37800000, v190
	v_cndmask_b32_e32 v190, v190, v191, vcc
	v_cmp_class_f32_e32 vcc, v186, v205
	s_nop 1
	v_cndmask_b32_e32 v186, v190, v186, vcc
	v_mul_f32_e32 v188, 0x3d112245, v186
	v_cvt_f32_i32_e32 v46, v46
	v_cvt_f32_i32_e32 v47, v47
	v_cvt_f32_i32_e32 v48, v48
	v_cvt_f32_i32_e32 v49, v49
	v_pk_mul_f32 v[142:143], v[222:223], v[188:189] op_sel_hi:[1,0]
	v_pk_mul_f32 v[144:145], v[224:225], v[188:189] op_sel_hi:[1,0]
	v_pk_fma_f32 v[154:155], v[142:143], v[46:47], v[206:207]
	v_pk_fma_f32 v[156:157], v[144:145], v[48:49], v[208:209]
	v_mul_f32_e32 v154, 0xbfb8aa3b, v154
	v_mul_f32_e32 v155, 0xbfb8aa3b, v155
	v_mul_f32_e32 v156, 0xbfb8aa3b, v156
	v_mul_f32_e32 v157, 0xbfb8aa3b, v157
	v_exp_f32_e32 v154, v154
	v_exp_f32_e32 v155, v155
	v_exp_f32_e32 v156, v156
	v_exp_f32_e32 v157, v157
	v_lshlrev_b32_e32 v146, 16, v170
	v_and_b32_e32 v147, 0xffff0000, v170
	v_lshlrev_b32_e32 v148, 16, v171
	v_and_b32_e32 v149, 0xffff0000, v171
	v_add_f32_e32 v154, 1.0, v154
	v_add_f32_e32 v155, 1.0, v155
	v_add_f32_e32 v156, 1.0, v156
	v_add_f32_e32 v157, 1.0, v157
	v_rcp_f32_e32 v154, v154
	v_rcp_f32_e32 v155, v155
	v_rcp_f32_e32 v156, v156
	v_rcp_f32_e32 v157, v157
	v_lshlrev_b32_e32 v150, 16, v178
	v_and_b32_e32 v151, 0xffff0000, v178
	v_lshlrev_b32_e32 v152, 16, v179
	v_and_b32_e32 v153, 0xffff0000, v179
	v_pk_fma_f32 v[46:47], v[154:155], v[150:151], v[146:147]
	v_pk_fma_f32 v[48:49], v[156:157], v[152:153], v[148:149]
	v_pk_mul_f32 v[194:195], v[46:47], v[46:47]
	v_pk_mul_f32 v[196:197], v[48:49], v[48:49]
	v_cvt_f32_i32_e32 v42, v42
	v_cvt_f32_i32_e32 v43, v43
	v_cvt_f32_i32_e32 v44, v44
	v_cvt_f32_i32_e32 v45, v45
	v_pk_mul_f32 v[142:143], v[226:227], v[188:189] op_sel_hi:[1,0]
	v_pk_mul_f32 v[144:145], v[228:229], v[188:189] op_sel_hi:[1,0]
	v_pk_fma_f32 v[154:155], v[142:143], v[42:43], v[210:211]
	v_pk_fma_f32 v[156:157], v[144:145], v[44:45], v[212:213]
	v_mul_f32_e32 v154, 0xbfb8aa3b, v154
	v_mul_f32_e32 v155, 0xbfb8aa3b, v155
	v_mul_f32_e32 v156, 0xbfb8aa3b, v156
	v_mul_f32_e32 v157, 0xbfb8aa3b, v157
	v_exp_f32_e32 v154, v154
	v_exp_f32_e32 v155, v155
	v_exp_f32_e32 v156, v156
	v_exp_f32_e32 v157, v157
	v_lshlrev_b32_e32 v146, 16, v172
	v_and_b32_e32 v147, 0xffff0000, v172
	v_lshlrev_b32_e32 v148, 16, v173
	v_and_b32_e32 v149, 0xffff0000, v173
	v_add_f32_e32 v154, 1.0, v154
	v_add_f32_e32 v155, 1.0, v155
	v_add_f32_e32 v156, 1.0, v156
	v_add_f32_e32 v157, 1.0, v157
	v_rcp_f32_e32 v154, v154
	v_rcp_f32_e32 v155, v155
	v_rcp_f32_e32 v156, v156
	v_rcp_f32_e32 v157, v157
	v_lshlrev_b32_e32 v150, 16, v180
	v_and_b32_e32 v151, 0xffff0000, v180
	v_lshlrev_b32_e32 v152, 16, v181
	v_and_b32_e32 v153, 0xffff0000, v181
	v_pk_fma_f32 v[42:43], v[154:155], v[150:151], v[146:147]
	v_pk_fma_f32 v[44:45], v[156:157], v[152:153], v[148:149]
	v_pk_fma_f32 v[194:195], v[42:43], v[42:43], v[194:195]
	v_pk_fma_f32 v[196:197], v[44:45], v[44:45], v[196:197]
	v_cvt_f32_i32_e32 v38, v38
	v_cvt_f32_i32_e32 v39, v39
	v_cvt_f32_i32_e32 v40, v40
	v_cvt_f32_i32_e32 v41, v41
	v_pk_mul_f32 v[142:143], v[230:231], v[188:189] op_sel_hi:[1,0]
	v_pk_mul_f32 v[144:145], v[232:233], v[188:189] op_sel_hi:[1,0]
	v_pk_fma_f32 v[154:155], v[142:143], v[38:39], v[214:215]
	v_pk_fma_f32 v[156:157], v[144:145], v[40:41], v[216:217]
	v_mul_f32_e32 v154, 0xbfb8aa3b, v154
	v_mul_f32_e32 v155, 0xbfb8aa3b, v155
	v_mul_f32_e32 v156, 0xbfb8aa3b, v156
	v_mul_f32_e32 v157, 0xbfb8aa3b, v157
	v_exp_f32_e32 v154, v154
	v_exp_f32_e32 v155, v155
	v_exp_f32_e32 v156, v156
	v_exp_f32_e32 v157, v157
	v_lshlrev_b32_e32 v146, 16, v174
	v_and_b32_e32 v147, 0xffff0000, v174
	v_lshlrev_b32_e32 v148, 16, v175
	v_and_b32_e32 v149, 0xffff0000, v175
	v_add_f32_e32 v154, 1.0, v154
	v_add_f32_e32 v155, 1.0, v155
	v_add_f32_e32 v156, 1.0, v156
	v_add_f32_e32 v157, 1.0, v157
	v_rcp_f32_e32 v154, v154
	v_rcp_f32_e32 v155, v155
	v_rcp_f32_e32 v156, v156
	v_rcp_f32_e32 v157, v157
	v_lshlrev_b32_e32 v150, 16, v182
	v_and_b32_e32 v151, 0xffff0000, v182
	v_lshlrev_b32_e32 v152, 16, v183
	v_and_b32_e32 v153, 0xffff0000, v183
	v_pk_fma_f32 v[38:39], v[154:155], v[150:151], v[146:147]
	v_pk_fma_f32 v[40:41], v[156:157], v[152:153], v[148:149]
	v_pk_fma_f32 v[194:195], v[38:39], v[38:39], v[194:195]
	v_pk_fma_f32 v[196:197], v[40:41], v[40:41], v[196:197]
	v_cvt_f32_i32_e32 v34, v34
	v_cvt_f32_i32_e32 v35, v35
	v_cvt_f32_i32_e32 v36, v36
	v_cvt_f32_i32_e32 v37, v37
	v_pk_mul_f32 v[142:143], v[234:235], v[188:189] op_sel_hi:[1,0]
	v_pk_mul_f32 v[144:145], v[236:237], v[188:189] op_sel_hi:[1,0]
	v_pk_fma_f32 v[154:155], v[142:143], v[34:35], v[218:219]
	v_pk_fma_f32 v[156:157], v[144:145], v[36:37], v[220:221]
	v_mul_f32_e32 v154, 0xbfb8aa3b, v154
	v_mul_f32_e32 v155, 0xbfb8aa3b, v155
	v_mul_f32_e32 v156, 0xbfb8aa3b, v156
	v_mul_f32_e32 v157, 0xbfb8aa3b, v157
	v_exp_f32_e32 v154, v154
	v_exp_f32_e32 v155, v155
	v_exp_f32_e32 v156, v156
	v_exp_f32_e32 v157, v157
	v_lshlrev_b32_e32 v146, 16, v176
	v_and_b32_e32 v147, 0xffff0000, v176
	v_lshlrev_b32_e32 v148, 16, v177
	v_and_b32_e32 v149, 0xffff0000, v177
	v_add_f32_e32 v154, 1.0, v154
	v_add_f32_e32 v155, 1.0, v155
	v_add_f32_e32 v156, 1.0, v156
	v_add_f32_e32 v157, 1.0, v157
	v_rcp_f32_e32 v154, v154
	v_rcp_f32_e32 v155, v155
	v_rcp_f32_e32 v156, v156
	v_rcp_f32_e32 v157, v157
	v_lshlrev_b32_e32 v150, 16, v184
	v_and_b32_e32 v151, 0xffff0000, v184
	v_lshlrev_b32_e32 v152, 16, v185
	v_and_b32_e32 v153, 0xffff0000, v185
	v_pk_fma_f32 v[34:35], v[154:155], v[150:151], v[146:147]
	v_pk_fma_f32 v[36:37], v[156:157], v[152:153], v[148:149]
	v_pk_fma_f32 v[194:195], v[34:35], v[34:35], v[194:195]
	v_pk_fma_f32 v[196:197], v[36:37], v[36:37], v[196:197]
	v_add_f32_e32 v194, v194, v195
	v_add_f32_e32 v196, v196, v197
	v_add_f32_e32 v194, v194, v196
	ds_bpermute_b32 v195, v58, v194
	s_waitcnt lgkmcnt(0)
; __device__ __forceinline__ f32x4 acc_i2f(const f32x4 a) { return __builtin_convertvector(__builtin_bit_cast(i32x4, a), f32x4); }
;     __device__ __forceinline__ void operator()(const f32x4 (&acc)[2][2][4][2], const pg8::Unit& u, int wr, int wc, int fr, int fq) const {
;     ...
;                 for (int mm = 0; mm < 2; ++mm) { const int m = 2 * mp + mm, row = row0 + ai * 128 + m * 16; f32x4 ssv = {0.f, 0.f, 0.f, 0.f}; const float sa = (QCLIP / 127.f) * sqrtf(q1v[mm] * (1.f / DM) + EPS);
; #pragma unroll
;                     for (int bj = 0; bj < 2; ++bj) { const size_t off = (size_t)row * DM + col0 + bj * 128;
;                         f32x4 p0, p1, x0, x1; unpack8v(pr[mm][bj], p0, p1); unpack8v(hr[mm][bj], x0, x1);
;                         const f32x4 g0 = acc_i2f(acc[ai][bj][m][0]) * (sb[bj][0] * sa) + bv[bj][0], g1 = acc_i2f(acc[ai][bj][m][1]) * (sb[bj][1] * sa) + bv[bj][1];
;                         const f32x4 h0 = x0 + p0 * sigm4(g0), h1 = x1 + p1 * sigm4(g1);
;                         *(f32x4*)(H + off) = h0; *(f32x4*)(H + off + 4) = h1;
;                         ssv = ssv + h0 * h0; ssv = ssv + h1 * h1; }
;                     float ss = (ssv[0] + ssv[1]) + (ssv[2] + ssv[3]);
;                     ss += __shfl_xor(ss, 16); ss += __shfl_xor(ss, 32);
;                     if (fq == 0) unsafeAtomicAdd(rss3 + row, ss); }
	v_add_f32_e32 v194, v194, v195
	ds_bpermute_b32 v195, v59, v194
	s_waitcnt lgkmcnt(0)
	v_add_f32_e32 v194, v194, v195
	s_and_saveexec_b64 s[32:33], s[6:7]
	global_atomic_add_f32 v54, v194, s[70:71] offset:576
	s_or_b64 exec, exec, s[32:33]
	global_load_dword v67, v54, s[68:69] offset:704
	global_load_dwordx4 v[170:173], v56, s[86:87]
	global_load_dwordx4 v[174:177], v56, s[86:87] offset:256
	global_load_dwordx4 v[178:181], v56, s[88:89]
	global_load_dwordx4 v[182:185], v56, s[88:89] offset:256
	s_waitcnt vmcnt(6)
	v_fmamk_f32 v186, v66, 0x39800000, v204
	v_mul_f32_e32 v187, 0x4f800000, v186
	v_cmp_gt_f32_e32 vcc, s67, v186
	s_nop 1
	v_cndmask_b32_e32 v186, v186, v187, vcc
	v_sqrt_f32_e32 v190, v186
	s_nop 0
	v_add_u32_e32 v191, -1, v190
	v_add_u32_e32 v192, 1, v190
	v_fma_f32 v193, -v191, v190, v186
	v_fma_f32 v187, -v192, v190, v186
	v_cmp_ge_f32_e64 s[10:11], 0, v193
	s_nop 1
	v_cndmask_b32_e64 v190, v190, v191, s[10:11]
	v_cmp_lt_f32_e64 s[10:11], 0, v187
	s_nop 1
	v_cndmask_b32_e64 v190, v190, v192, s[10:11]
	v_mul_f32_e32 v191, 0x37800000, v190
	v_cndmask_b32_e32 v190, v190, v191, vcc
	v_cmp_class_f32_e32 vcc, v186, v205
	s_nop 1
	v_cndmask_b32_e32 v186, v190, v186, vcc
	v_mul_f32_e32 v188, 0x3d112245, v186
	v_cvt_f32_i32_e32 v30, v30
	v_cvt_f32_i32_e32 v31, v31
	v_cvt_f32_i32_e32 v32, v32
	v_cvt_f32_i32_e32 v33, v33
	v_pk_mul_f32 v[142:143], v[222:223], v[188:189] op_sel_hi:[1,0]
	v_pk_mul_f32 v[144:145], v[224:225], v[188:189] op_sel_hi:[1,0]
	v_pk_fma_f32 v[154:155], v[142:143], v[30:31], v[206:207]
	v_pk_fma_f32 v[156:157], v[144:145], v[32:33], v[208:209]
	v_mul_f32_e32 v154, 0xbfb8aa3b, v154
	v_mul_f32_e32 v155, 0xbfb8aa3b, v155
	v_mul_f32_e32 v156, 0xbfb8aa3b, v156
	v_mul_f32_e32 v157, 0xbfb8aa3b, v157
	v_exp_f32_e32 v154, v154
	v_exp_f32_e32 v155, v155
	v_exp_f32_e32 v156, v156
	v_exp_f32_e32 v157, v157
	v_lshlrev_b32_e32 v146, 16, v238
	v_and_b32_e32 v147, 0xffff0000, v238
	v_lshlrev_b32_e32 v148, 16, v239
	v_and_b32_e32 v149, 0xffff0000, v239
	v_add_f32_e32 v154, 1.0, v154
	v_add_f32_e32 v155, 1.0, v155
	v_add_f32_e32 v156, 1.0, v156
	v_add_f32_e32 v157, 1.0, v157
	v_rcp_f32_e32 v154, v154
	v_rcp_f32_e32 v155, v155
	v_rcp_f32_e32 v156, v156
	v_rcp_f32_e32 v157, v157
	v_lshlrev_b32_e32 v150, 16, v246
	v_and_b32_e32 v151, 0xffff0000, v246
	v_lshlrev_b32_e32 v152, 16, v247
	v_and_b32_e32 v153, 0xffff0000, v247
	v_pk_fma_f32 v[30:31], v[154:155], v[150:151], v[146:147]
	v_pk_fma_f32 v[32:33], v[156:157], v[152:153], v[148:149]
	v_pk_mul_f32 v[194:195], v[30:31], v[30:31]
	v_pk_mul_f32 v[196:197], v[32:33], v[32:33]
	v_cvt_f32_i32_e32 v26, v26
	v_cvt_f32_i32_e32 v27, v27
	v_cvt_f32_i32_e32 v28, v28
	v_cvt_f32_i32_e32 v29, v29
	v_pk_mul_f32 v[142:143], v[226:227], v[188:189] op_sel_hi:[1,0]
	v_pk_mul_f32 v[144:145], v[228:229], v[188:189] op_sel_hi:[1,0]
	v_pk_fma_f32 v[154:155], v[142:143], v[26:27], v[210:211]
	v_pk_fma_f32 v[156:157], v[144:145], v[28:29], v[212:213]
	v_mul_f32_e32 v154, 0xbfb8aa3b, v154
	v_mul_f32_e32 v155, 0xbfb8aa3b, v155
	v_mul_f32_e32 v156, 0xbfb8aa3b, v156
	v_mul_f32_e32 v157, 0xbfb8aa3b, v157
	v_exp_f32_e32 v154, v154
	v_exp_f32_e32 v155, v155
	v_exp_f32_e32 v156, v156
	v_exp_f32_e32 v157, v157
	v_lshlrev_b32_e32 v146, 16, v240
	v_and_b32_e32 v147, 0xffff0000, v240
	v_lshlrev_b32_e32 v148, 16, v241
	v_and_b32_e32 v149, 0xffff0000, v241
	v_add_f32_e32 v154, 1.0, v154
	v_add_f32_e32 v155, 1.0, v155
	v_add_f32_e32 v156, 1.0, v156
	v_add_f32_e32 v157, 1.0, v157
	v_rcp_f32_e32 v154, v154
	v_rcp_f32_e32 v155, v155
	v_rcp_f32_e32 v156, v156
	v_rcp_f32_e32 v157, v157
	v_lshlrev_b32_e32 v150, 16, v248
	v_and_b32_e32 v151, 0xffff0000, v248
	v_lshlrev_b32_e32 v152, 16, v249
	v_and_b32_e32 v153, 0xffff0000, v249
	v_pk_fma_f32 v[26:27], v[154:155], v[150:151], v[146:147]
	v_pk_fma_f32 v[28:29], v[156:157], v[152:153], v[148:149]
	v_pk_fma_f32 v[194:195], v[26:27], v[26:27], v[194:195]
	v_pk_fma_f32 v[196:197], v[28:29], v[28:29], v[196:197]
	v_cvt_f32_i32_e32 v22, v22
	v_cvt_f32_i32_e32 v23, v23
	v_cvt_f32_i32_e32 v24, v24
	v_cvt_f32_i32_e32 v25, v25
	v_pk_mul_f32 v[142:143], v[230:231], v[188:189] op_sel_hi:[1,0]
	v_pk_mul_f32 v[144:145], v[232:233], v[188:189] op_sel_hi:[1,0]
	v_pk_fma_f32 v[154:155], v[142:143], v[22:23], v[214:215]
	v_pk_fma_f32 v[156:157], v[144:145], v[24:25], v[216:217]
	v_mul_f32_e32 v154, 0xbfb8aa3b, v154
	v_mul_f32_e32 v155, 0xbfb8aa3b, v155
	v_mul_f32_e32 v156, 0xbfb8aa3b, v156
	v_mul_f32_e32 v157, 0xbfb8aa3b, v157
	v_exp_f32_e32 v154, v154
	v_exp_f32_e32 v155, v155
	v_exp_f32_e32 v156, v156
	v_exp_f32_e32 v157, v157
	v_lshlrev_b32_e32 v146, 16, v242
	v_and_b32_e32 v147, 0xffff0000, v242
	v_lshlrev_b32_e32 v148, 16, v243
	v_and_b32_e32 v149, 0xffff0000, v243
	v_add_f32_e32 v154, 1.0, v154
	v_add_f32_e32 v155, 1.0, v155
	v_add_f32_e32 v156, 1.0, v156
	v_add_f32_e32 v157, 1.0, v157
	v_rcp_f32_e32 v154, v154
	v_rcp_f32_e32 v155, v155
	v_rcp_f32_e32 v156, v156
	v_rcp_f32_e32 v157, v157
	v_lshlrev_b32_e32 v150, 16, v250
	v_and_b32_e32 v151, 0xffff0000, v250
	v_lshlrev_b32_e32 v152, 16, v251
	v_and_b32_e32 v153, 0xffff0000, v251
	v_pk_fma_f32 v[22:23], v[154:155], v[150:151], v[146:147]
	v_pk_fma_f32 v[24:25], v[156:157], v[152:153], v[148:149]
	v_pk_fma_f32 v[194:195], v[22:23], v[22:23], v[194:195]
	v_pk_fma_f32 v[196:197], v[24:25], v[24:25], v[196:197]
	v_cvt_f32_i32_e32 v18, v18
	v_cvt_f32_i32_e32 v19, v19
	v_cvt_f32_i32_e32 v20, v20
	v_cvt_f32_i32_e32 v21, v21
	v_pk_mul_f32 v[142:143], v[234:235], v[188:189] op_sel_hi:[1,0]
	v_pk_mul_f32 v[144:145], v[236:237], v[188:189] op_sel_hi:[1,0]
	v_pk_fma_f32 v[154:155], v[142:143], v[18:19], v[218:219]
	v_pk_fma_f32 v[156:157], v[144:145], v[20:21], v[220:221]
	v_mul_f32_e32 v154, 0xbfb8aa3b, v154
	v_mul_f32_e32 v155, 0xbfb8aa3b, v155
	v_mul_f32_e32 v156, 0xbfb8aa3b, v156
	v_mul_f32_e32 v157, 0xbfb8aa3b, v157
	v_exp_f32_e32 v154, v154
	v_exp_f32_e32 v155, v155
	v_exp_f32_e32 v156, v156
	v_exp_f32_e32 v157, v157
	v_lshlrev_b32_e32 v146, 16, v244
	v_and_b32_e32 v147, 0xffff0000, v244
	v_lshlrev_b32_e32 v148, 16, v245
	v_and_b32_e32 v149, 0xffff0000, v245
	v_add_f32_e32 v154, 1.0, v154
	v_add_f32_e32 v155, 1.0, v155
	v_add_f32_e32 v156, 1.0, v156
	v_add_f32_e32 v157, 1.0, v157
	v_rcp_f32_e32 v154, v154
	v_rcp_f32_e32 v155, v155
	v_rcp_f32_e32 v156, v156
	v_rcp_f32_e32 v157, v157
	v_lshlrev_b32_e32 v150, 16, v252
	v_and_b32_e32 v151, 0xffff0000, v252
	v_lshlrev_b32_e32 v152, 16, v253
	v_and_b32_e32 v153, 0xffff0000, v253
	v_pk_fma_f32 v[18:19], v[154:155], v[150:151], v[146:147]
	v_pk_fma_f32 v[20:21], v[156:157], v[152:153], v[148:149]
	v_pk_fma_f32 v[194:195], v[18:19], v[18:19], v[194:195]
	v_pk_fma_f32 v[196:197], v[20:21], v[20:21], v[196:197]
	v_add_f32_e32 v194, v194, v195
	v_add_f32_e32 v196, v196, v197
	v_add_f32_e32 v194, v194, v196
	ds_bpermute_b32 v195, v58, v194
	s_waitcnt lgkmcnt(0)
; __device__ __forceinline__ f32x4 acc_i2f(const f32x4 a) { return __builtin_convertvector(__builtin_bit_cast(i32x4, a), f32x4); }
;     __device__ __forceinline__ void operator()(const f32x4 (&acc)[2][2][4][2], const pg8::Unit& u, int wr, int wc, int fr, int fq) const {
;     ...
;                 for (int mm = 0; mm < 2; ++mm) { const int m = 2 * mp + mm, row = row0 + ai * 128 + m * 16; f32x4 ssv = {0.f, 0.f, 0.f, 0.f}; const float sa = (QCLIP / 127.f) * sqrtf(q1v[mm] * (1.f / DM) + EPS);
; #pragma unroll
;                     for (int bj = 0; bj < 2; ++bj) { const size_t off = (size_t)row * DM + col0 + bj * 128;
;                         f32x4 p0, p1, x0, x1; unpack8v(pr[mm][bj], p0, p1); unpack8v(hr[mm][bj], x0, x1);
;                         const f32x4 g0 = acc_i2f(acc[ai][bj][m][0]) * (sb[bj][0] * sa) + bv[bj][0], g1 = acc_i2f(acc[ai][bj][m][1]) * (sb[bj][1] * sa) + bv[bj][1];
;                         const f32x4 h0 = x0 + p0 * sigm4(g0), h1 = x1 + p1 * sigm4(g1);
;                         *(f32x4*)(H + off) = h0; *(f32x4*)(H + off + 4) = h1;
;                         ssv = ssv + h0 * h0; ssv = ssv + h1 * h1; }
;                     float ss = (ssv[0] + ssv[1]) + (ssv[2] + ssv[3]);
;                     ss += __shfl_xor(ss, 16); ss += __shfl_xor(ss, 32);
;                     if (fq == 0) unsafeAtomicAdd(rss3 + row, ss); }
	v_add_f32_e32 v194, v194, v195
	ds_bpermute_b32 v195, v59, v194
	s_waitcnt lgkmcnt(0)
	v_add_f32_e32 v194, v194, v195
	s_and_saveexec_b64 s[32:33], s[6:7]
	global_atomic_add_f32 v54, v194, s[70:71] offset:640
	s_or_b64 exec, exec, s[32:33]
	s_waitcnt vmcnt(1)
	v_fmamk_f32 v186, v67, 0x39800000, v204
	v_mul_f32_e32 v187, 0x4f800000, v186
	v_cmp_gt_f32_e32 vcc, s67, v186
	s_nop 1
	v_cndmask_b32_e32 v186, v186, v187, vcc
	v_sqrt_f32_e32 v190, v186
	s_nop 0
	v_add_u32_e32 v191, -1, v190
	v_add_u32_e32 v192, 1, v190
	v_fma_f32 v193, -v191, v190, v186
	v_fma_f32 v187, -v192, v190, v186
	v_cmp_ge_f32_e64 s[10:11], 0, v193
	s_nop 1
	v_cndmask_b32_e64 v190, v190, v191, s[10:11]
	v_cmp_lt_f32_e64 s[10:11], 0, v187
	s_nop 1
	v_cndmask_b32_e64 v190, v190, v192, s[10:11]
	v_mul_f32_e32 v191, 0x37800000, v190
	v_cndmask_b32_e32 v190, v190, v191, vcc
	v_cmp_class_f32_e32 vcc, v186, v205
	s_nop 1
	v_cndmask_b32_e32 v186, v190, v186, vcc
	v_mul_f32_e32 v188, 0x3d112245, v186
	v_cvt_f32_i32_e32 v14, v14
	v_cvt_f32_i32_e32 v15, v15
	v_cvt_f32_i32_e32 v16, v16
	v_cvt_f32_i32_e32 v17, v17
	v_pk_mul_f32 v[142:143], v[222:223], v[188:189] op_sel_hi:[1,0]
	v_pk_mul_f32 v[144:145], v[224:225], v[188:189] op_sel_hi:[1,0]
	v_pk_fma_f32 v[154:155], v[142:143], v[14:15], v[206:207]
	v_pk_fma_f32 v[156:157], v[144:145], v[16:17], v[208:209]
	v_mul_f32_e32 v154, 0xbfb8aa3b, v154
	v_mul_f32_e32 v155, 0xbfb8aa3b, v155
	v_mul_f32_e32 v156, 0xbfb8aa3b, v156
	v_mul_f32_e32 v157, 0xbfb8aa3b, v157
	v_exp_f32_e32 v154, v154
	v_exp_f32_e32 v155, v155
	v_exp_f32_e32 v156, v156
	v_exp_f32_e32 v157, v157
	v_lshlrev_b32_e32 v146, 16, v170
	v_and_b32_e32 v147, 0xffff0000, v170
	v_lshlrev_b32_e32 v148, 16, v171
	v_and_b32_e32 v149, 0xffff0000, v171
	v_add_f32_e32 v154, 1.0, v154
	v_add_f32_e32 v155, 1.0, v155
	v_add_f32_e32 v156, 1.0, v156
	v_add_f32_e32 v157, 1.0, v157
	v_rcp_f32_e32 v154, v154
	v_rcp_f32_e32 v155, v155
	v_rcp_f32_e32 v156, v156
	v_rcp_f32_e32 v157, v157
	v_lshlrev_b32_e32 v150, 16, v178
	v_and_b32_e32 v151, 0xffff0000, v178
	v_lshlrev_b32_e32 v152, 16, v179
	v_and_b32_e32 v153, 0xffff0000, v179
	v_pk_fma_f32 v[14:15], v[154:155], v[150:151], v[146:147]
	v_pk_fma_f32 v[16:17], v[156:157], v[152:153], v[148:149]
	v_pk_mul_f32 v[194:195], v[14:15], v[14:15]
	v_pk_mul_f32 v[196:197], v[16:17], v[16:17]
	v_cvt_f32_i32_e32 v10, v10
	v_cvt_f32_i32_e32 v11, v11
	v_cvt_f32_i32_e32 v12, v12
	v_cvt_f32_i32_e32 v13, v13
	v_pk_mul_f32 v[142:143], v[226:227], v[188:189] op_sel_hi:[1,0]
	v_pk_mul_f32 v[144:145], v[228:229], v[188:189] op_sel_hi:[1,0]
	v_pk_fma_f32 v[154:155], v[142:143], v[10:11], v[210:211]
	v_pk_fma_f32 v[156:157], v[144:145], v[12:13], v[212:213]
	v_mul_f32_e32 v154, 0xbfb8aa3b, v154
	v_mul_f32_e32 v155, 0xbfb8aa3b, v155
	v_mul_f32_e32 v156, 0xbfb8aa3b, v156
	v_mul_f32_e32 v157, 0xbfb8aa3b, v157
	v_exp_f32_e32 v154, v154
	v_exp_f32_e32 v155, v155
	v_exp_f32_e32 v156, v156
	v_exp_f32_e32 v157, v157
	v_lshlrev_b32_e32 v146, 16, v172
	v_and_b32_e32 v147, 0xffff0000, v172
	v_lshlrev_b32_e32 v148, 16, v173
	v_and_b32_e32 v149, 0xffff0000, v173
	v_add_f32_e32 v154, 1.0, v154
	v_add_f32_e32 v155, 1.0, v155
	v_add_f32_e32 v156, 1.0, v156
	v_add_f32_e32 v157, 1.0, v157
	v_rcp_f32_e32 v154, v154
	v_rcp_f32_e32 v155, v155
	v_rcp_f32_e32 v156, v156
	v_rcp_f32_e32 v157, v157
	v_lshlrev_b32_e32 v150, 16, v180
	v_and_b32_e32 v151, 0xffff0000, v180
	v_lshlrev_b32_e32 v152, 16, v181
	v_and_b32_e32 v153, 0xffff0000, v181
	v_pk_fma_f32 v[10:11], v[154:155], v[150:151], v[146:147]
	v_pk_fma_f32 v[12:13], v[156:157], v[152:153], v[148:149]
	v_pk_fma_f32 v[194:195], v[10:11], v[10:11], v[194:195]
	v_pk_fma_f32 v[196:197], v[12:13], v[12:13], v[196:197]
	v_cvt_f32_i32_e32 v6, v6
	v_cvt_f32_i32_e32 v7, v7
	v_cvt_f32_i32_e32 v8, v8
	v_cvt_f32_i32_e32 v9, v9
	v_pk_mul_f32 v[142:143], v[230:231], v[188:189] op_sel_hi:[1,0]
	v_pk_mul_f32 v[144:145], v[232:233], v[188:189] op_sel_hi:[1,0]
	v_pk_fma_f32 v[154:155], v[142:143], v[6:7], v[214:215]
	v_pk_fma_f32 v[156:157], v[144:145], v[8:9], v[216:217]
	v_mul_f32_e32 v154, 0xbfb8aa3b, v154
	v_mul_f32_e32 v155, 0xbfb8aa3b, v155
	v_mul_f32_e32 v156, 0xbfb8aa3b, v156
	v_mul_f32_e32 v157, 0xbfb8aa3b, v157
	v_exp_f32_e32 v154, v154
	v_exp_f32_e32 v155, v155
	v_exp_f32_e32 v156, v156
	v_exp_f32_e32 v157, v157
	v_lshlrev_b32_e32 v146, 16, v174
	v_and_b32_e32 v147, 0xffff0000, v174
	v_lshlrev_b32_e32 v148, 16, v175
	v_and_b32_e32 v149, 0xffff0000, v175
	v_add_f32_e32 v154, 1.0, v154
	v_add_f32_e32 v155, 1.0, v155
	v_add_f32_e32 v156, 1.0, v156
	v_add_f32_e32 v157, 1.0, v157
	v_rcp_f32_e32 v154, v154
	v_rcp_f32_e32 v155, v155
	v_rcp_f32_e32 v156, v156
	v_rcp_f32_e32 v157, v157
	v_lshlrev_b32_e32 v150, 16, v182
	v_and_b32_e32 v151, 0xffff0000, v182
	v_lshlrev_b32_e32 v152, 16, v183
	v_and_b32_e32 v153, 0xffff0000, v183
	v_pk_fma_f32 v[6:7], v[154:155], v[150:151], v[146:147]
	v_pk_fma_f32 v[8:9], v[156:157], v[152:153], v[148:149]
	v_pk_fma_f32 v[194:195], v[6:7], v[6:7], v[194:195]
	v_pk_fma_f32 v[196:197], v[8:9], v[8:9], v[196:197]
	v_cvt_f32_i32_e32 v2, v2
	v_cvt_f32_i32_e32 v3, v3
	v_cvt_f32_i32_e32 v4, v4
	v_cvt_f32_i32_e32 v5, v5
	v_pk_mul_f32 v[142:143], v[234:235], v[188:189] op_sel_hi:[1,0]
	v_pk_mul_f32 v[144:145], v[236:237], v[188:189] op_sel_hi:[1,0]
	v_pk_fma_f32 v[154:155], v[142:143], v[2:3], v[218:219]
	v_pk_fma_f32 v[156:157], v[144:145], v[4:5], v[220:221]
	v_mul_f32_e32 v154, 0xbfb8aa3b, v154
	v_mul_f32_e32 v155, 0xbfb8aa3b, v155
	v_mul_f32_e32 v156, 0xbfb8aa3b, v156
	v_mul_f32_e32 v157, 0xbfb8aa3b, v157
	v_exp_f32_e32 v154, v154
	v_exp_f32_e32 v155, v155
	v_exp_f32_e32 v156, v156
	v_exp_f32_e32 v157, v157
	v_lshlrev_b32_e32 v146, 16, v176
	v_and_b32_e32 v147, 0xffff0000, v176
	v_lshlrev_b32_e32 v148, 16, v177
	v_and_b32_e32 v149, 0xffff0000, v177
	v_add_f32_e32 v154, 1.0, v154
	v_add_f32_e32 v155, 1.0, v155
	v_add_f32_e32 v156, 1.0, v156
	v_add_f32_e32 v157, 1.0, v157
	v_rcp_f32_e32 v154, v154
	v_rcp_f32_e32 v155, v155
	v_rcp_f32_e32 v156, v156
	v_rcp_f32_e32 v157, v157
	v_lshlrev_b32_e32 v150, 16, v184
	v_and_b32_e32 v151, 0xffff0000, v184
	v_lshlrev_b32_e32 v152, 16, v185
	v_and_b32_e32 v153, 0xffff0000, v185
	v_pk_fma_f32 v[2:3], v[154:155], v[150:151], v[146:147]
	v_pk_fma_f32 v[4:5], v[156:157], v[152:153], v[148:149]
	v_pk_fma_f32 v[194:195], v[2:3], v[2:3], v[194:195]
	v_pk_fma_f32 v[196:197], v[4:5], v[4:5], v[196:197]
	v_add_f32_e32 v194, v194, v195
	v_add_f32_e32 v196, v196, v197
	v_add_f32_e32 v194, v194, v196
	ds_bpermute_b32 v195, v58, v194
	s_waitcnt lgkmcnt(0)
	v_add_f32_e32 v194, v194, v195
	ds_bpermute_b32 v195, v59, v194
	s_waitcnt lgkmcnt(0)
	v_add_f32_e32 v194, v194, v195
	s_and_saveexec_b64 s[32:33], s[6:7]
	global_atomic_add_f32 v54, v194, s[70:71] offset:704
	s_or_b64 exec, exec, s[32:33]
	s_waitcnt vmcnt(0)
	s_barrier
; __device__ __forceinline__ void ph_final_norm(float* H, const float* __restrict__ rowss, const float* __restrict__ g, size_t gt, size_t NGT) {
;     const size_t n4 = (size_t)SEQ * DM / 4;
;     f32x4* h4 = (f32x4*)H;
;     for (size_t i0 = gt; i0 < n4; i0 += 8 * NGT) {
;         f32x4 v[8]; float rs[8];
; #pragma unroll
;         for (int k = 0; k < 8; ++k) { const size_t i = i0 + k * NGT; v[k] = h4[i]; rs[k] = rowss[i >> 10]; }
; #pragma unroll
;         for (int k = 0; k < 8; ++k) { const size_t i = i0 + k * NGT; const f32x4 gg = ((const f32x4*)g)[i & 1023]; h4[i] = v[k] * rsqrtf(rs[k] * (1.f / DM) + EPS) * gg; }
	s_load_dwordx2 s[100:101], s[92:93], 0xa8
	s_lshl_b32 s48, s98, 7
	s_add_u32 s50, s26, s48
	s_addc_u32 s51, s27, 0
	s_add_u32 s50, s50, 0x10000
	s_addc_u32 s51, s51, 0
	s_and_saveexec_b64 s[52:53], s[96:97]
	s_cbranch_execz .Lfz_poll_done
	v_mov_b32_e32 v60, 0
	v_mov_b32_e32 v61, 1
	global_atomic_add v60, v61, s[50:51]
	s_mov_b32 s49, 0

; __device__ __forceinline__ void ph_final_norm(float* H, const float* __restrict__ rowss, const float* __restrict__ g, size_t gt, size_t NGT) {
;     ...
;     for (size_t i0 = gt; i0 < n4; i0 += 8 * NGT) {
;         f32x4 v[8]; float rs[8];
; #pragma unroll
;         for (int k = 0; k < 8; ++k) { const size_t i = i0 + k * NGT; v[k] = h4[i]; rs[k] = rowss[i >> 10]; }
; #pragma unroll
;         for (int k = 0; k < 8; ++k) { const size_t i = i0 + k * NGT; const f32x4 gg = ((const f32x4*)g)[i & 1023]; h4[i] = v[k] * rsqrtf(rs[k] * (1.f / DM) + EPS) * gg; }
.Lfz_poll_done:
	s_or_b64 exec, exec, s[52:53]
	s_barrier
	global_load_dword v142, v54, s[70:71] sc1
	global_load_dword v144, v54, s[70:71] offset:64 sc1
	global_load_dword v146, v54, s[70:71] offset:128 sc1
	global_load_dword v148, v54, s[70:71] offset:192 sc1
	global_load_dword v150, v54, s[70:71] offset:512 sc1
	global_load_dword v152, v54, s[70:71] offset:576 sc1
	global_load_dword v154, v54, s[70:71] offset:640 sc1
	global_load_dword v156, v54, s[70:71] offset:704 sc1
	s_waitcnt lgkmcnt(0)
	s_lshl_b32 s48, s99, 10
	s_add_u32 s100, s100, s48
	s_addc_u32 s101, s101, 0
	global_load_dwordx4 v[206:209], v55, s[100:101]
	global_load_dwordx4 v[210:213], v55, s[100:101] offset:16
	global_load_dwordx4 v[214:217], v55, s[100:101] offset:512
	global_load_dwordx4 v[218:221], v55, s[100:101] offset:528
	s_mov_b64 s[90:91], s[84:85]
	s_waitcnt vmcnt(0)
	v_fmamk_f32 v142, v142, 0x39800000, v204
	v_fmamk_f32 v144, v144, 0x39800000, v204
	v_fmamk_f32 v146, v146, 0x39800000, v204
	v_fmamk_f32 v148, v148, 0x39800000, v204
	v_fmamk_f32 v150, v150, 0x39800000, v204
	v_fmamk_f32 v152, v152, 0x39800000, v204
	v_fmamk_f32 v154, v154, 0x39800000, v204
	v_fmamk_f32 v156, v156, 0x39800000, v204
	v_rsq_f32_e32 v142, v142
	v_rsq_f32_e32 v144, v144
	v_rsq_f32_e32 v146, v146
	v_rsq_f32_e32 v148, v148
	v_rsq_f32_e32 v150, v150
	v_rsq_f32_e32 v152, v152
	v_rsq_f32_e32 v154, v154
	v_rsq_f32_e32 v156, v156
	s_nop 0
	v_pk_mul_f32 v[50:51], v[50:51], v[142:143] op_sel_hi:[1,0]
	v_pk_mul_f32 v[52:53], v[52:53], v[142:143] op_sel_hi:[1,0]
	v_pk_mul_f32 v[50:51], v[50:51], v[206:207]
	v_pk_mul_f32 v[52:53], v[52:53], v[208:209]
	v_pk_mul_f32 v[138:139], v[138:139], v[142:143] op_sel_hi:[1,0]
	v_pk_mul_f32 v[140:141], v[140:141], v[142:143] op_sel_hi:[1,0]
	v_pk_mul_f32 v[138:139], v[138:139], v[210:211]
	v_pk_mul_f32 v[140:141], v[140:141], v[212:213]
	v_pk_mul_f32 v[134:135], v[134:135], v[142:143] op_sel_hi:[1,0]
	v_pk_mul_f32 v[136:137], v[136:137], v[142:143] op_sel_hi:[1,0]
	v_pk_mul_f32 v[134:135], v[134:135], v[214:215]
	v_pk_mul_f32 v[136:137], v[136:137], v[216:217]
	v_pk_mul_f32 v[130:131], v[130:131], v[142:143] op_sel_hi:[1,0]
	v_pk_mul_f32 v[132:133], v[132:133], v[142:143] op_sel_hi:[1,0]
	v_pk_mul_f32 v[130:131], v[130:131], v[218:219]
	v_pk_mul_f32 v[132:133], v[132:133], v[220:221]
	global_store_dwordx4 v57, v[50:53], s[90:91]
	global_store_dwordx4 v57, v[138:141], s[90:91] offset:16
	global_store_dwordx4 v57, v[134:137], s[90:91] offset:512
	global_store_dwordx4 v57, v[130:133], s[90:91] offset:528
	s_add_u32 s90, s90, 0x40000
	s_addc_u32 s91, s91, 0
	v_pk_mul_f32 v[126:127], v[126:127], v[144:145] op_sel_hi:[1,0]
	v_pk_mul_f32 v[128:129], v[128:129], v[144:145] op_sel_hi:[1,0]
	v_pk_mul_f32 v[126:127], v[126:127], v[206:207]
	v_pk_mul_f32 v[128:129], v[128:129], v[208:209]
	v_pk_mul_f32 v[122:123], v[122:123], v[144:145] op_sel_hi:[1,0]
	v_pk_mul_f32 v[124:125], v[124:125], v[144:145] op_sel_hi:[1,0]
	v_pk_mul_f32 v[122:123], v[122:123], v[210:211]
	v_pk_mul_f32 v[124:125], v[124:125], v[212:213]
	v_pk_mul_f32 v[118:119], v[118:119], v[144:145] op_sel_hi:[1,0]
	v_pk_mul_f32 v[120:121], v[120:121], v[144:145] op_sel_hi:[1,0]
	v_pk_mul_f32 v[118:119], v[118:119], v[214:215]
	v_pk_mul_f32 v[120:121], v[120:121], v[216:217]
	v_pk_mul_f32 v[114:115], v[114:115], v[144:145] op_sel_hi:[1,0]
	v_pk_mul_f32 v[116:117], v[116:117], v[144:145] op_sel_hi:[1,0]
	v_pk_mul_f32 v[114:115], v[114:115], v[218:219]
	v_pk_mul_f32 v[116:117], v[116:117], v[220:221]
	global_store_dwordx4 v57, v[126:129], s[90:91]
	global_store_dwordx4 v57, v[122:125], s[90:91] offset:16
	global_store_dwordx4 v57, v[118:121], s[90:91] offset:512
	global_store_dwordx4 v57, v[114:117], s[90:91] offset:528
	s_add_u32 s90, s90, 0x40000
	s_addc_u32 s91, s91, 0
	v_pk_mul_f32 v[110:111], v[110:111], v[146:147] op_sel_hi:[1,0]
	v_pk_mul_f32 v[112:113], v[112:113], v[146:147] op_sel_hi:[1,0]
	v_pk_mul_f32 v[110:111], v[110:111], v[206:207]
	v_pk_mul_f32 v[112:113], v[112:113], v[208:209]
	v_pk_mul_f32 v[106:107], v[106:107], v[146:147] op_sel_hi:[1,0]
	v_pk_mul_f32 v[108:109], v[108:109], v[146:147] op_sel_hi:[1,0]
	v_pk_mul_f32 v[106:107], v[106:107], v[210:211]
	v_pk_mul_f32 v[108:109], v[108:109], v[212:213]
	v_pk_mul_f32 v[102:103], v[102:103], v[146:147] op_sel_hi:[1,0]
	v_pk_mul_f32 v[104:105], v[104:105], v[146:147] op_sel_hi:[1,0]
	v_pk_mul_f32 v[102:103], v[102:103], v[214:215]
	v_pk_mul_f32 v[104:105], v[104:105], v[216:217]
	v_pk_mul_f32 v[98:99], v[98:99], v[146:147] op_sel_hi:[1,0]
	v_pk_mul_f32 v[100:101], v[100:101], v[146:147] op_sel_hi:[1,0]
	v_pk_mul_f32 v[98:99], v[98:99], v[218:219]
	v_pk_mul_f32 v[100:101], v[100:101], v[220:221]
	global_store_dwordx4 v57, v[110:113], s[90:91]
	global_store_dwordx4 v57, v[106:109], s[90:91] offset:16
	global_store_dwordx4 v57, v[102:105], s[90:91] offset:512
	global_store_dwordx4 v57, v[98:101], s[90:91] offset:528
	s_add_u32 s90, s90, 0x40000
	s_addc_u32 s91, s91, 0
	v_pk_mul_f32 v[94:95], v[94:95], v[148:149] op_sel_hi:[1,0]
	v_pk_mul_f32 v[96:97], v[96:97], v[148:149] op_sel_hi:[1,0]
	v_pk_mul_f32 v[94:95], v[94:95], v[206:207]
	v_pk_mul_f32 v[96:97], v[96:97], v[208:209]
	v_pk_mul_f32 v[90:91], v[90:91], v[148:149] op_sel_hi:[1,0]
; __device__ __forceinline__ void ph_final_norm(float* H, const float* __restrict__ rowss, const float* __restrict__ g, size_t gt, size_t NGT) {
;     ...
;         for (int k = 0; k < 8; ++k) { const size_t i = i0 + k * NGT; v[k] = h4[i]; rs[k] = rowss[i >> 10]; }
; #pragma unroll
;         for (int k = 0; k < 8; ++k) { const size_t i = i0 + k * NGT; const f32x4 gg = ((const f32x4*)g)[i & 1023]; h4[i] = v[k] * rsqrtf(rs[k] * (1.f / DM) + EPS) * gg; }
	v_pk_mul_f32 v[92:93], v[92:93], v[148:149] op_sel_hi:[1,0]
	v_pk_mul_f32 v[90:91], v[90:91], v[210:211]
	v_pk_mul_f32 v[92:93], v[92:93], v[212:213]
	v_pk_mul_f32 v[86:87], v[86:87], v[148:149] op_sel_hi:[1,0]
	v_pk_mul_f32 v[88:89], v[88:89], v[148:149] op_sel_hi:[1,0]
	v_pk_mul_f32 v[86:87], v[86:87], v[214:215]
	v_pk_mul_f32 v[88:89], v[88:89], v[216:217]
	v_pk_mul_f32 v[82:83], v[82:83], v[148:149] op_sel_hi:[1,0]
	v_pk_mul_f32 v[84:85], v[84:85], v[148:149] op_sel_hi:[1,0]
	v_pk_mul_f32 v[82:83], v[82:83], v[218:219]
	v_pk_mul_f32 v[84:85], v[84:85], v[220:221]
	global_store_dwordx4 v57, v[94:97], s[90:91]
	global_store_dwordx4 v57, v[90:93], s[90:91] offset:16
	global_store_dwordx4 v57, v[86:89], s[90:91] offset:512
	global_store_dwordx4 v57, v[82:85], s[90:91] offset:528
	s_add_u32 s90, s90, 0x140000
	s_addc_u32 s91, s91, 0
	v_pk_mul_f32 v[78:79], v[78:79], v[150:151] op_sel_hi:[1,0]
	v_pk_mul_f32 v[80:81], v[80:81], v[150:151] op_sel_hi:[1,0]
	v_pk_mul_f32 v[78:79], v[78:79], v[206:207]
	v_pk_mul_f32 v[80:81], v[80:81], v[208:209]
	v_pk_mul_f32 v[74:75], v[74:75], v[150:151] op_sel_hi:[1,0]
	v_pk_mul_f32 v[76:77], v[76:77], v[150:151] op_sel_hi:[1,0]
	v_pk_mul_f32 v[74:75], v[74:75], v[210:211]
	v_pk_mul_f32 v[76:77], v[76:77], v[212:213]
	v_pk_mul_f32 v[70:71], v[70:71], v[150:151] op_sel_hi:[1,0]
	v_pk_mul_f32 v[72:73], v[72:73], v[150:151] op_sel_hi:[1,0]
	v_pk_mul_f32 v[70:71], v[70:71], v[214:215]
	v_pk_mul_f32 v[72:73], v[72:73], v[216:217]
	v_pk_mul_f32 v[62:63], v[62:63], v[150:151] op_sel_hi:[1,0]
	v_pk_mul_f32 v[64:65], v[64:65], v[150:151] op_sel_hi:[1,0]
	v_pk_mul_f32 v[62:63], v[62:63], v[218:219]
	v_pk_mul_f32 v[64:65], v[64:65], v[220:221]
	global_store_dwordx4 v57, v[78:81], s[90:91]
	global_store_dwordx4 v57, v[74:77], s[90:91] offset:16
	global_store_dwordx4 v57, v[70:73], s[90:91] offset:512
	global_store_dwordx4 v57, v[62:65], s[90:91] offset:528
	s_add_u32 s90, s90, 0x40000
	s_addc_u32 s91, s91, 0
	v_pk_mul_f32 v[46:47], v[46:47], v[152:153] op_sel_hi:[1,0]
	v_pk_mul_f32 v[48:49], v[48:49], v[152:153] op_sel_hi:[1,0]
	v_pk_mul_f32 v[46:47], v[46:47], v[206:207]
	v_pk_mul_f32 v[48:49], v[48:49], v[208:209]
	v_pk_mul_f32 v[42:43], v[42:43], v[152:153] op_sel_hi:[1,0]
	v_pk_mul_f32 v[44:45], v[44:45], v[152:153] op_sel_hi:[1,0]
	v_pk_mul_f32 v[42:43], v[42:43], v[210:211]
	v_pk_mul_f32 v[44:45], v[44:45], v[212:213]
	v_pk_mul_f32 v[38:39], v[38:39], v[152:153] op_sel_hi:[1,0]
	v_pk_mul_f32 v[40:41], v[40:41], v[152:153] op_sel_hi:[1,0]
	v_pk_mul_f32 v[38:39], v[38:39], v[214:215]
	v_pk_mul_f32 v[40:41], v[40:41], v[216:217]
	v_pk_mul_f32 v[34:35], v[34:35], v[152:153] op_sel_hi:[1,0]
	v_pk_mul_f32 v[36:37], v[36:37], v[152:153] op_sel_hi:[1,0]
	v_pk_mul_f32 v[34:35], v[34:35], v[218:219]
	v_pk_mul_f32 v[36:37], v[36:37], v[220:221]
	global_store_dwordx4 v57, v[46:49], s[90:91]
	global_store_dwordx4 v57, v[42:45], s[90:91] offset:16
	global_store_dwordx4 v57, v[38:41], s[90:91] offset:512
	global_store_dwordx4 v57, v[34:37], s[90:91] offset:528
	s_add_u32 s90, s90, 0x40000
	s_addc_u32 s91, s91, 0
	v_pk_mul_f32 v[30:31], v[30:31], v[154:155] op_sel_hi:[1,0]
	v_pk_mul_f32 v[32:33], v[32:33], v[154:155] op_sel_hi:[1,0]
	v_pk_mul_f32 v[30:31], v[30:31], v[206:207]
	v_pk_mul_f32 v[32:33], v[32:33], v[208:209]
	v_pk_mul_f32 v[26:27], v[26:27], v[154:155] op_sel_hi:[1,0]
	v_pk_mul_f32 v[28:29], v[28:29], v[154:155] op_sel_hi:[1,0]
	v_pk_mul_f32 v[26:27], v[26:27], v[210:211]
	v_pk_mul_f32 v[28:29], v[28:29], v[212:213]
	v_pk_mul_f32 v[22:23], v[22:23], v[154:155] op_sel_hi:[1,0]
	v_pk_mul_f32 v[24:25], v[24:25], v[154:155] op_sel_hi:[1,0]
	v_pk_mul_f32 v[22:23], v[22:23], v[214:215]
	v_pk_mul_f32 v[24:25], v[24:25], v[216:217]
	v_pk_mul_f32 v[18:19], v[18:19], v[154:155] op_sel_hi:[1,0]
	v_pk_mul_f32 v[20:21], v[20:21], v[154:155] op_sel_hi:[1,0]
	v_pk_mul_f32 v[18:19], v[18:19], v[218:219]
	v_pk_mul_f32 v[20:21], v[20:21], v[220:221]
	global_store_dwordx4 v57, v[30:33], s[90:91]
	global_store_dwordx4 v57, v[26:29], s[90:91] offset:16
	global_store_dwordx4 v57, v[22:25], s[90:91] offset:512
	global_store_dwordx4 v57, v[18:21], s[90:91] offset:528
	s_add_u32 s90, s90, 0x40000
	s_addc_u32 s91, s91, 0
	v_pk_mul_f32 v[14:15], v[14:15], v[156:157] op_sel_hi:[1,0]
	v_pk_mul_f32 v[16:17], v[16:17], v[156:157] op_sel_hi:[1,0]
	v_pk_mul_f32 v[14:15], v[14:15], v[206:207]
	v_pk_mul_f32 v[16:17], v[16:17], v[208:209]
	v_pk_mul_f32 v[10:11], v[10:11], v[156:157] op_sel_hi:[1,0]
	v_pk_mul_f32 v[12:13], v[12:13], v[156:157] op_sel_hi:[1,0]
	v_pk_mul_f32 v[10:11], v[10:11], v[210:211]
	v_pk_mul_f32 v[12:13], v[12:13], v[212:213]
	v_pk_mul_f32 v[6:7], v[6:7], v[156:157] op_sel_hi:[1,0]
	v_pk_mul_f32 v[8:9], v[8:9], v[156:157] op_sel_hi:[1,0]
	v_pk_mul_f32 v[6:7], v[6:7], v[214:215]
	v_pk_mul_f32 v[8:9], v[8:9], v[216:217]
	v_pk_mul_f32 v[2:3], v[2:3], v[156:157] op_sel_hi:[1,0]
	v_pk_mul_f32 v[4:5], v[4:5], v[156:157] op_sel_hi:[1,0]
	v_pk_mul_f32 v[2:3], v[2:3], v[218:219]
	v_pk_mul_f32 v[4:5], v[4:5], v[220:221]
	global_store_dwordx4 v57, v[14:17], s[90:91]
	global_store_dwordx4 v57, v[10:13], s[90:91] offset:16
	global_store_dwordx4 v57, v[6:9], s[90:91] offset:512
	global_store_dwordx4 v57, v[2:5], s[90:91] offset:528
	s_nop 1
	s_branch .Lp8_epi_done

; #define PG8_BAR __builtin_amdgcn_s_barrier()
; template <class Epi, class Sched, bool ALIGN_EPI = false, bool SP2 = false>
; __device__ __forceinline__ void gemm_phase(PG8_LAS unsigned char* lds, const Gemm g, const Sched& S, const Epi& E) {
;     ...
;         if constexpr (ALIGN_EPI) { if (wr == 0) PG8_BAR; }
;         if constexpr (!Epi::AFTER_DRAIN) { E(acc, cur, wr, wc, fr, fq); S.done(cur); }
;         if (!has_next) break;
; #pragma unroll
;         for (int a = 0; a < 2; ++a)
; #pragma unroll
;             for (int b = 0; b < 2; ++b)
; #pragma unroll
;                 for (int m = 0; m < 4; ++m)
; #pragma unroll
;                     for (int n = 0; n < 2; ++n) acc[a][b][m][n] = (f32x4){0.f, 0.f, 0.f, 0.f};
;         cur = nxt; cA = nA; cB = nB; ++ui;
;         if constexpr (ALIGN_EPI) { if (wr == 1) PG8_BAR; }
;     }
.Lp8_epi_done:
	s_andn2_b64 vcc, exec, s[8:9]
	s_mov_b64 s[8:9], -1
	s_cbranch_vccnz .LBB0_1449
	s_andn2_b64 vcc, exec, s[20:21]
	s_cbranch_vccnz .LBB0_1448
	s_barrier
	s_branch .LBB0_1448

; #define SEAM(k) do { if (IN(k) && IN((k) + 1)) xcd_barrier(bar); } while (0)
; __device__ __forceinline__ void xcd_barrier(const XcdBarrier& b) {
;     asm volatile("s_waitcnt vmcnt(0)" ::: "memory");
;     __syncthreads();
;     if (threadIdx.x == 0) {
;         unsigned* bar = b.bar;
;         __builtin_amdgcn_s_waitcnt(0);
;         unsigned nloc = b.st[0], nx = b.st[1];
;         if (nloc == 0u) { xcd_barrier_complete(bar, b.x, nloc, nx); b.st[0] = nloc; b.st[1] = nx; }
; __global__ void __launch_bounds__(512, 2) k_fwd(Args a_unused) {
;     ...
;     SEAM(8);
;     if (IN(9)) { PH_IDS(); ph_final_norm(ap->out, ctl + CW_RSS3, ap->in[21], gt, NGT); }
.LBB0_1480:
	s_cmpk_eq_i32 s74, 0x100
	s_cbranch_scc1 .LBB0_1538
	s_cmp_gt_i32 s77, 9
	s_cselect_b64 s[6:7], -1, 0
	s_and_b64 s[4:5], s[16:17], s[6:7]
	s_andn2_b64 vcc, exec, s[4:5]
	s_cbranch_vccnz .LBB0_1534
	s_waitcnt vmcnt(0)
	s_waitcnt vmcnt(0) lgkmcnt(0)
	s_barrier
	s_and_saveexec_b64 s[8:9], s[96:97]
	s_cbranch_execz .LBB0_1533
	s_add_i32 s1, 0, 0x20160
	v_mov_b32_e32 v1, s1
	s_waitcnt vmcnt(0) expcnt(0) lgkmcnt(0)
	ds_read_b32 v3, v1
	s_add_i32 s1, 0, 0x20164
	v_mov_b32_e32 v1, s1
	ds_read_b32 v1, v1
	s_waitcnt lgkmcnt(1)
	v_cmp_ne_u32_e32 vcc, 0, v3
	s_cbranch_vccnz .LBB0_1497
	s_load_dwordx2 s[12:13], s[94:95], 0x4
	s_add_u32 s4, s78, 0x1000
	s_addc_u32 s5, s79, 0
	s_add_u32 s10, s78, 0x1100
	s_addc_u32 s11, s79, 0
	s_waitcnt lgkmcnt(0)
	s_mul_i32 s1, s12, s74
	s_add_u32 s12, s78, 0x1200
	s_mul_i32 s1, s1, s13
	s_addc_u32 s13, s79, 0
	s_add_u32 s14, s78, 0x1300
	s_addc_u32 s15, s79, 0
	s_mov_b32 s3, 1
	v_mov_b32_e32 v17, 0
	s_branch .LBB0_1485
